# plus: attn loop waits skip prior stores; conv0-conv1 seam arrive-only; mixin gammas via LDS; conv spectral loop rewritten with all loads up front
# speedup vs baseline: 1.0511x; 1.0326x over previous
; __device__ __forceinline__ c2 cmul(c2 a, c2 b) { return (c2){a.x * b.x - a.y * b.y, a.x * b.y + a.y * b.x}; }
; __device__ __forceinline__ void phase_conv(const Params& p, int o, unsigned char* smem, int wave) {
;     ...
;             for (int q = 0; q < 8; ++q) {
;                 c2 Z[8], Y[8];
; #pragma unroll
;                 for (int j = 0; j < 8; ++j) { Z[j] = sZ[(j * 8 + q) * 512 + tid]; Y[j] = (c2){0.f, 0.f}; }
; #pragma unroll
;                 for (int d = -7; d <= 7; ++d) { const c2 kd = sK[((d + 7) * 8 + q) * 512 + tid];
; #pragma unroll
;                     for (int i = 0; i < 8; ++i) if (i - d >= 0 && i - d < 8) Y[i] += cmul(Z[i - d], kd); }
; #pragma unroll
;                 for (int a = 0; a < 4; ++a) sZ[(a * 8 + q) * 512 + tid] = (c2){Y[2 * a].x - Y[2 * a + 1].y, Y[2 * a].y + Y[2 * a + 1].x};
;             }
.LBB0_594:
	s_waitcnt vmcnt(16)
	v_add_u32_e32 v234, s60, v113
	v_lshlrev_b32_e32 v234, 3, v234
	v_add_u32_e32 v235, 0x8000, v234
	v_add_u32_e32 v236, 0x10000, v234
	v_add_u32_e32 v237, 0x18000, v234
	v_add_u32_e32 v238, 0x20000, v234
	v_add_u32_e32 v239, 0x28000, v234
	v_add_u32_e32 v240, 0x30000, v234
	v_add_u32_e32 v241, 0x38000, v234
	v_add_u32_e32 v242, 0x40000, v234
	v_add_u32_e32 v243, 0x48000, v234
	v_add_u32_e32 v244, 0x50000, v234
	v_add_u32_e32 v245, 0x58000, v234
	v_add_u32_e32 v246, 0x60000, v234
	v_add_u32_e32 v247, 0x68000, v234
	v_add_u32_e32 v248, 0x70000, v234
	global_load_dwordx2 v[210:211], v234, s[18:19]
	global_load_dwordx2 v[212:213], v235, s[18:19]
	global_load_dwordx2 v[214:215], v236, s[18:19]
	global_load_dwordx2 v[216:217], v237, s[18:19]
	global_load_dwordx2 v[218:219], v238, s[18:19]
	global_load_dwordx2 v[220:221], v239, s[18:19]
	global_load_dwordx2 v[222:223], v240, s[18:19]
	global_load_dwordx2 v[224:225], v241, s[18:19]
	global_load_dwordx2 v[28:29], v234, s[8:9]
	global_load_dwordx2 v[30:31], v235, s[8:9]
	global_load_dwordx2 v[32:33], v236, s[8:9]
	global_load_dwordx2 v[34:35], v237, s[8:9]
	global_load_dwordx2 v[36:37], v238, s[8:9]
	global_load_dwordx2 v[38:39], v239, s[8:9]
	global_load_dwordx2 v[40:41], v240, s[8:9]
	global_load_dwordx2 v[42:43], v241, s[8:9]
	global_load_dwordx2 v[44:45], v242, s[8:9]
	global_load_dwordx2 v[46:47], v243, s[8:9]
	global_load_dwordx2 v[48:49], v244, s[8:9]
	global_load_dwordx2 v[50:51], v245, s[8:9]
	global_load_dwordx2 v[52:53], v246, s[8:9]
	global_load_dwordx2 v[54:55], v247, s[8:9]
	global_load_dwordx2 v[90:91], v248, s[8:9]
	v_mov_b32_e32 v0, 0
	v_mov_b32_e32 v1, 0
	v_mov_b32_e32 v2, 0
	v_mov_b32_e32 v3, 0
	v_mov_b32_e32 v4, 0
	v_mov_b32_e32 v5, 0
	v_mov_b32_e32 v6, 0
	v_mov_b32_e32 v7, 0
	v_mov_b32_e32 v8, 0
	v_mov_b32_e32 v9, 0
	v_mov_b32_e32 v10, 0
	v_mov_b32_e32 v11, 0
	v_mov_b32_e32 v12, 0
	v_mov_b32_e32 v13, 0
	v_mov_b32_e32 v14, 0
	v_mov_b32_e32 v15, 0
	s_waitcnt vmcnt(14)
	v_fmac_f32_e32 v0, v224, v28
	v_fmac_f32_e32 v1, v224, v29
	v_fma_f32 v0, -v225, v29, v0
	v_fmac_f32_e32 v1, v225, v28
	s_waitcnt vmcnt(13)
	v_fmac_f32_e32 v0, v222, v30
	v_fmac_f32_e32 v2, v224, v30
	v_fmac_f32_e32 v1, v222, v31
	v_fmac_f32_e32 v3, v224, v31
	v_fma_f32 v0, -v223, v31, v0
	v_fma_f32 v2, -v225, v31, v2
	v_fmac_f32_e32 v1, v223, v30
	v_fmac_f32_e32 v3, v225, v30
	s_waitcnt vmcnt(12)
	v_fmac_f32_e32 v0, v220, v32
	v_fmac_f32_e32 v2, v222, v32
	v_fmac_f32_e32 v4, v224, v32
	v_fmac_f32_e32 v1, v220, v33
	v_fmac_f32_e32 v3, v222, v33
	v_fmac_f32_e32 v5, v224, v33
	v_fma_f32 v0, -v221, v33, v0
	v_fma_f32 v2, -v223, v33, v2
	v_fma_f32 v4, -v225, v33, v4
	v_fmac_f32_e32 v1, v221, v32
	v_fmac_f32_e32 v3, v223, v32
	v_fmac_f32_e32 v5, v225, v32
	s_waitcnt vmcnt(11)
	v_fmac_f32_e32 v0, v218, v34
	v_fmac_f32_e32 v2, v220, v34
	v_fmac_f32_e32 v4, v222, v34
	v_fmac_f32_e32 v6, v224, v34
	v_fmac_f32_e32 v1, v218, v35
	v_fmac_f32_e32 v3, v220, v35
	v_fmac_f32_e32 v5, v222, v35
	v_fmac_f32_e32 v7, v224, v35
	v_fma_f32 v0, -v219, v35, v0
	v_fma_f32 v2, -v221, v35, v2
	v_fma_f32 v4, -v223, v35, v4
	v_fma_f32 v6, -v225, v35, v6
	v_fmac_f32_e32 v1, v219, v34
	v_fmac_f32_e32 v3, v221, v34
	v_fmac_f32_e32 v5, v223, v34
	v_fmac_f32_e32 v7, v225, v34
	s_waitcnt vmcnt(10)
	v_fmac_f32_e32 v0, v216, v36
	v_fmac_f32_e32 v2, v218, v36
	v_fmac_f32_e32 v4, v220, v36
	v_fmac_f32_e32 v6, v222, v36
	v_fmac_f32_e32 v8, v224, v36
	v_fmac_f32_e32 v1, v216, v37
	v_fmac_f32_e32 v3, v218, v37
	v_fmac_f32_e32 v5, v220, v37
	v_fmac_f32_e32 v7, v222, v37
	v_fmac_f32_e32 v9, v224, v37
	v_fma_f32 v0, -v217, v37, v0
	v_fma_f32 v2, -v219, v37, v2
	v_fma_f32 v4, -v221, v37, v4
	v_fma_f32 v6, -v223, v37, v6
	v_fma_f32 v8, -v225, v37, v8
	v_fmac_f32_e32 v1, v217, v36
	v_fmac_f32_e32 v3, v219, v36
	v_fmac_f32_e32 v5, v221, v36
	v_fmac_f32_e32 v7, v223, v36
	v_fmac_f32_e32 v9, v225, v36
	s_waitcnt vmcnt(9)
	v_fmac_f32_e32 v0, v214, v38
	v_fmac_f32_e32 v2, v216, v38
	v_fmac_f32_e32 v4, v218, v38
	v_fmac_f32_e32 v6, v220, v38
	v_fmac_f32_e32 v8, v222, v38
	v_fmac_f32_e32 v10, v224, v38
	v_fmac_f32_e32 v1, v214, v39
	v_fmac_f32_e32 v3, v216, v39
	v_fmac_f32_e32 v5, v218, v39
	v_fmac_f32_e32 v7, v220, v39
	v_fmac_f32_e32 v9, v222, v39
	v_fmac_f32_e32 v11, v224, v39
	v_fma_f32 v0, -v215, v39, v0
	v_fma_f32 v2, -v217, v39, v2
	v_fma_f32 v4, -v219, v39, v4
	v_fma_f32 v6, -v221, v39, v6
	v_fma_f32 v8, -v223, v39, v8
	v_fma_f32 v10, -v225, v39, v10
	v_fmac_f32_e32 v1, v215, v38
	v_fmac_f32_e32 v3, v217, v38
	v_fmac_f32_e32 v5, v219, v38
	v_fmac_f32_e32 v7, v221, v38
	v_fmac_f32_e32 v9, v223, v38
	v_fmac_f32_e32 v11, v225, v38
	s_waitcnt vmcnt(8)
	v_fmac_f32_e32 v0, v212, v40
	v_fmac_f32_e32 v2, v214, v40
	v_fmac_f32_e32 v4, v216, v40
	v_fmac_f32_e32 v6, v218, v40
	v_fmac_f32_e32 v8, v220, v40
	v_fmac_f32_e32 v10, v222, v40
	v_fmac_f32_e32 v12, v224, v40
	v_fmac_f32_e32 v1, v212, v41
	v_fmac_f32_e32 v3, v214, v41
	v_fmac_f32_e32 v5, v216, v41
	v_fmac_f32_e32 v7, v218, v41
	v_fmac_f32_e32 v9, v220, v41
	v_fmac_f32_e32 v11, v222, v41
	v_fmac_f32_e32 v13, v224, v41
	v_fma_f32 v0, -v213, v41, v0
	v_fma_f32 v2, -v215, v41, v2
	v_fma_f32 v4, -v217, v41, v4
	v_fma_f32 v6, -v219, v41, v6
	v_fma_f32 v8, -v221, v41, v8
	v_fma_f32 v10, -v223, v41, v10
	v_fma_f32 v12, -v225, v41, v12
	v_fmac_f32_e32 v1, v213, v40
	v_fmac_f32_e32 v3, v215, v40
	v_fmac_f32_e32 v5, v217, v40
	v_fmac_f32_e32 v7, v219, v40
	v_fmac_f32_e32 v9, v221, v40
	v_fmac_f32_e32 v11, v223, v40
	v_fmac_f32_e32 v13, v225, v40
	s_waitcnt vmcnt(7)
; __device__ __forceinline__ c2 cmul(c2 a, c2 b) { return (c2){a.x * b.x - a.y * b.y, a.x * b.y + a.y * b.x}; }
; __device__ __forceinline__ void phase_conv(const Params& p, int o, unsigned char* smem, int wave) {
;     ...
;                 for (int d = -7; d <= 7; ++d) { const c2 kd = sK[((d + 7) * 8 + q) * 512 + tid];
; #pragma unroll
;                     for (int i = 0; i < 8; ++i) if (i - d >= 0 && i - d < 8) Y[i] += cmul(Z[i - d], kd); }
; #pragma unroll
;                 for (int a = 0; a < 4; ++a) sZ[(a * 8 + q) * 512 + tid] = (c2){Y[2 * a].x - Y[2 * a + 1].y, Y[2 * a].y + Y[2 * a + 1].x};
;             }
	v_fmac_f32_e32 v0, v210, v42
	v_fmac_f32_e32 v2, v212, v42
	v_fmac_f32_e32 v4, v214, v42
	v_fmac_f32_e32 v6, v216, v42
	v_fmac_f32_e32 v8, v218, v42
	v_fmac_f32_e32 v10, v220, v42
	v_fmac_f32_e32 v12, v222, v42
	v_fmac_f32_e32 v14, v224, v42
	v_fmac_f32_e32 v1, v210, v43
	v_fmac_f32_e32 v3, v212, v43
	v_fmac_f32_e32 v5, v214, v43
	v_fmac_f32_e32 v7, v216, v43
	v_fmac_f32_e32 v9, v218, v43
	v_fmac_f32_e32 v11, v220, v43
	v_fmac_f32_e32 v13, v222, v43
	v_fmac_f32_e32 v15, v224, v43
	v_fma_f32 v0, -v211, v43, v0
	v_fma_f32 v2, -v213, v43, v2
	v_fma_f32 v4, -v215, v43, v4
	v_fma_f32 v6, -v217, v43, v6
	v_fma_f32 v8, -v219, v43, v8
	v_fma_f32 v10, -v221, v43, v10
	v_fma_f32 v12, -v223, v43, v12
	v_fma_f32 v14, -v225, v43, v14
	v_fmac_f32_e32 v1, v211, v42
	v_fmac_f32_e32 v3, v213, v42
	v_fmac_f32_e32 v5, v215, v42
	v_fmac_f32_e32 v7, v217, v42
	v_fmac_f32_e32 v9, v219, v42
	v_fmac_f32_e32 v11, v221, v42
	v_fmac_f32_e32 v13, v223, v42
	v_fmac_f32_e32 v15, v225, v42
	s_waitcnt vmcnt(6)
	v_fmac_f32_e32 v2, v210, v44
	v_fmac_f32_e32 v4, v212, v44
	v_fmac_f32_e32 v6, v214, v44
	v_fmac_f32_e32 v8, v216, v44
	v_fmac_f32_e32 v10, v218, v44
	v_fmac_f32_e32 v12, v220, v44
	v_fmac_f32_e32 v14, v222, v44
	v_fmac_f32_e32 v3, v210, v45
	v_fmac_f32_e32 v5, v212, v45
	v_fmac_f32_e32 v7, v214, v45
	v_fmac_f32_e32 v9, v216, v45
	v_fmac_f32_e32 v11, v218, v45
	v_fmac_f32_e32 v13, v220, v45
	v_fmac_f32_e32 v15, v222, v45
	v_fma_f32 v2, -v211, v45, v2
	v_fma_f32 v4, -v213, v45, v4
	v_fma_f32 v6, -v215, v45, v6
	v_fma_f32 v8, -v217, v45, v8
	v_fma_f32 v10, -v219, v45, v10
	v_fma_f32 v12, -v221, v45, v12
	v_fma_f32 v14, -v223, v45, v14
	v_fmac_f32_e32 v3, v211, v44
	v_fmac_f32_e32 v5, v213, v44
	v_fmac_f32_e32 v7, v215, v44
	v_fmac_f32_e32 v9, v217, v44
	v_fmac_f32_e32 v11, v219, v44
	v_fmac_f32_e32 v13, v221, v44
	v_fmac_f32_e32 v15, v223, v44
	s_waitcnt vmcnt(5)
	v_fmac_f32_e32 v4, v210, v46
	v_fmac_f32_e32 v6, v212, v46
	v_fmac_f32_e32 v8, v214, v46
	v_fmac_f32_e32 v10, v216, v46
	v_fmac_f32_e32 v12, v218, v46
	v_fmac_f32_e32 v14, v220, v46
	v_fmac_f32_e32 v5, v210, v47
	v_fmac_f32_e32 v7, v212, v47
	v_fmac_f32_e32 v9, v214, v47
	v_fmac_f32_e32 v11, v216, v47
	v_fmac_f32_e32 v13, v218, v47
	v_fmac_f32_e32 v15, v220, v47
	v_fma_f32 v4, -v211, v47, v4
	v_fma_f32 v6, -v213, v47, v6
	v_fma_f32 v8, -v215, v47, v8
	v_fma_f32 v10, -v217, v47, v10
	v_fma_f32 v12, -v219, v47, v12
	v_fma_f32 v14, -v221, v47, v14
	v_fmac_f32_e32 v5, v211, v46
	v_fmac_f32_e32 v7, v213, v46
	v_fmac_f32_e32 v9, v215, v46
	v_fmac_f32_e32 v11, v217, v46
	v_fmac_f32_e32 v13, v219, v46
	v_fmac_f32_e32 v15, v221, v46
	s_waitcnt vmcnt(4)
	v_fmac_f32_e32 v6, v210, v48
	v_fmac_f32_e32 v8, v212, v48
	v_fmac_f32_e32 v10, v214, v48
	v_fmac_f32_e32 v12, v216, v48
	v_fmac_f32_e32 v14, v218, v48
	v_fmac_f32_e32 v7, v210, v49
	v_fmac_f32_e32 v9, v212, v49
	v_fmac_f32_e32 v11, v214, v49
	v_fmac_f32_e32 v13, v216, v49
	v_fmac_f32_e32 v15, v218, v49
	v_fma_f32 v6, -v211, v49, v6
	v_fma_f32 v8, -v213, v49, v8
	v_fma_f32 v10, -v215, v49, v10
	v_fma_f32 v12, -v217, v49, v12
	v_fma_f32 v14, -v219, v49, v14
	v_fmac_f32_e32 v7, v211, v48
	v_fmac_f32_e32 v9, v213, v48
	v_fmac_f32_e32 v11, v215, v48
	v_fmac_f32_e32 v13, v217, v48
	v_fmac_f32_e32 v15, v219, v48
	s_waitcnt vmcnt(3)
	v_fmac_f32_e32 v8, v210, v50
	v_fmac_f32_e32 v10, v212, v50
	v_fmac_f32_e32 v12, v214, v50
	v_fmac_f32_e32 v14, v216, v50
	v_fmac_f32_e32 v9, v210, v51
	v_fmac_f32_e32 v11, v212, v51
	v_fmac_f32_e32 v13, v214, v51
	v_fmac_f32_e32 v15, v216, v51
	v_fma_f32 v8, -v211, v51, v8
	v_fma_f32 v10, -v213, v51, v10
	v_fma_f32 v12, -v215, v51, v12
	v_fma_f32 v14, -v217, v51, v14
	v_fmac_f32_e32 v9, v211, v50
	v_fmac_f32_e32 v11, v213, v50
	v_fmac_f32_e32 v13, v215, v50
	v_fmac_f32_e32 v15, v217, v50
	s_waitcnt vmcnt(2)
	v_fmac_f32_e32 v10, v210, v52
	v_fmac_f32_e32 v12, v212, v52
	v_fmac_f32_e32 v14, v214, v52
	v_fmac_f32_e32 v11, v210, v53
	v_fmac_f32_e32 v13, v212, v53
	v_fmac_f32_e32 v15, v214, v53
	v_fma_f32 v10, -v211, v53, v10
	v_fma_f32 v12, -v213, v53, v12
	v_fma_f32 v14, -v215, v53, v14
	v_fmac_f32_e32 v11, v211, v52
	v_fmac_f32_e32 v13, v213, v52
	v_fmac_f32_e32 v15, v215, v52
	s_waitcnt vmcnt(1)
	v_fmac_f32_e32 v12, v210, v54
	v_fmac_f32_e32 v14, v212, v54
	v_fmac_f32_e32 v13, v210, v55
	v_fmac_f32_e32 v15, v212, v55
	v_fma_f32 v12, -v211, v55, v12
	v_fma_f32 v14, -v213, v55, v14
	v_fmac_f32_e32 v13, v211, v54
	v_fmac_f32_e32 v15, v213, v54
	s_waitcnt vmcnt(0)
	v_fmac_f32_e32 v14, v210, v90
	v_fmac_f32_e32 v15, v210, v91
	v_fma_f32 v14, -v211, v91, v14
	v_fmac_f32_e32 v15, v211, v90
	v_sub_f32_e32 v0, v0, v3
	v_add_f32_e32 v1, v1, v2
	v_sub_f32_e32 v4, v4, v7
	v_add_f32_e32 v5, v5, v6
	v_sub_f32_e32 v8, v8, v11
	v_add_f32_e32 v9, v9, v10
	v_sub_f32_e32 v12, v12, v15
	v_add_f32_e32 v13, v13, v14
	global_store_dwordx2 v234, v[0:1], s[18:19]
	global_store_dwordx2 v235, v[4:5], s[18:19]
	global_store_dwordx2 v236, v[8:9], s[18:19]
	global_store_dwordx2 v237, v[12:13], s[18:19]
	s_addk_i32 s60, 0x200
	s_cmpk_eq_i32 s60, 0x1000
	s_cbranch_scc0 .LBB0_594
	global_load_dwordx4 v[0:3], v[20:21], off
	global_load_dwordx4 v[4:7], v[22:23], off
	global_load_dwordx4 v[8:11], v[24:25], off
	global_load_dwordx4 v[12:15], v[26:27], off
	v_cmp_lt_i16_sdwa s[40:41], v113, s94 src0_sel:BYTE_0 src1_sel:DWORD
	s_mov_b64 s[62:63], -1
	s_and_saveexec_b64 s[60:61], s[40:41]
	s_cbranch_execz .LBB0_599
	v_mov_b32_e32 v20, 0
	v_cmp_eq_u16_sdwa s[40:41], v113, v57 src0_sel:BYTE_0 src1_sel:DWORD
	s_mov_b64 s[70:71], 0
	v_mov_b32_e32 v21, 0
	v_mov_b32_e32 v22, 0
	s_and_saveexec_b64 s[62:63], s[40:41]
	s_cbranch_execz .LBB0_598
	v_add_co_u32_e32 v20, vcc, 0x20000, v16
	s_and_b64 s[70:71], s[42:43], exec
	s_nop 0
	v_addc_co_u32_e32 v21, vcc, 0, v17, vcc
	v_add_co_u32_e32 v22, vcc, 0x21000, v16
	global_load_ushort v20, v[20:21], off offset:4094
	s_nop 0
	v_addc_co_u32_e32 v23, vcc, 0, v17, vcc
	global_load_ushort v21, v[22:23], off offset:4094
	v_add_co_u32_e32 v22, vcc, 0x22000, v16
	s_nop 1
	v_addc_co_u32_e32 v23, vcc, 0, v17, vcc
	global_load_ushort v22, v[22:23], off offset:4094

; #define PH(k) if (lo <= (k) && (k) < hi) for (int rep_ = 0; rep_ <= ((REP_MASK >> (k)) & 1); ++rep_)
; #define SEAM(k) if (lo <= (k) && (k) + 1 < hi) grid_bar(barctr, (unsigned)((k) + 1 - lo) * gridDim.x, wave)
; __device__ __forceinline__ void grid_bar(unsigned* ctr, unsigned target, int wave) {
;     __builtin_amdgcn_s_waitcnt(0x0F70);
;     __syncthreads();
;     if (wave == 0) {
;         int l; asm volatile("v_mbcnt_lo_u32_b32 %0, -1, 0\n\tv_mbcnt_hi_u32_b32 %0, -1, %0" : "=v"(l));
;         if (l == 0) {
;             __builtin_amdgcn_fence(__ATOMIC_RELEASE, "agent");
;             __hip_atomic_fetch_add(ctr, 1u, __ATOMIC_RELAXED, __HIP_MEMORY_SCOPE_AGENT);
;             while (__hip_atomic_load(ctr, __ATOMIC_RELAXED, __HIP_MEMORY_SCOPE_AGENT) < target) __builtin_amdgcn_s_sleep(2);
;             __builtin_amdgcn_fence(__ATOMIC_ACQUIRE, "agent");
;         }
;     }
;     __syncthreads();
; }
; __global__ void __launch_bounds__(NTHR, 2) fwd_kernel(Params p) {
;     ...
;     for (int o = 0; o < 2; ++o) { PH(3 + o) { phase_conv(p, o, smem, wave); } SEAM(3 + o); }
.LBB0_706:
	s_or_b64 exec, exec, s[6:7]
	s_cmp_eq_u32 s41, 0
	s_cbranch_scc1 .LBB0_195
	v_readlane_b32 s4, v253, 61
	v_readlane_b32 s5, v253, 62
	s_sub_i32 s3, s3, s72
	s_mul_i32 s3, s3, s93
	s_nop 2
	global_load_dword v0, v57, s[4:5] sc1
	s_waitcnt vmcnt(0)
	v_cmp_le_u32_e32 vcc, s3, v0
	s_cbranch_vccnz .LBB0_195

; __device__ void phase_attn(const Params& p, unsigned char* smem, int wave) {
;     ...
;         const float slope = exp2f(-(float)(h + 1)) * (float)d * 1.4426950408889634f;
;         const int qi = i0 + 16 * w4 + ql;
;         float mx = -1e30f;
; #pragma unroll
;         for (int kt = 0; kt < 9; ++kt)
; #pragma unroll
;             for (int j = 0; j < 4; ++j) { const int rel = 16 * kt + 4 * gq + j - 64 - ql; const int jk = qi + rel;
;                 const bool relok = (kt == 0) ? (rel >= -64) : ((kt == 8) ? (rel <= 64) : true);
;                 const bool ok = relok && ((unsigned)jk < (unsigned)Ls);
;                 const float v = ok ? sc[kt][j] * 0.18033688011112042f - slope * fabsf((float)rel) : -1e30f;
;                 sc[kt][j] = v; mx = fmaxf(mx, v); }
.LBB0_718:
	s_or_b64 exec, exec, s[0:1]
	v_or_b32_e32 v12, s64, v44
	v_bfe_u32 v13, v44, 4, 2
	v_and_b32_e32 v66, 15, v44
	v_ashrrev_i32_e32 v12, 2, v12
	v_lshlrev_b32_e32 v141, 2, v13
	v_and_b32_e32 v67, -16, v12
	v_bfi_b32 v12, -16, v12, v44
	s_movk_i32 s33, 0x90
	v_sub_u32_e32 v142, v141, v66
	v_mul_lo_u32 v12, v12, s33
	v_lshl_add_u32 v14, v13, 4, 0
	v_subrev_u32_e32 v143, 64, v142
	v_subrev_u32_e32 v144, 63, v142
	v_add_u32_e32 v140, v14, v12
	v_bfe_u32 v12, v44, 2, 2
	v_lshlrev_b32_e32 v14, 3, v44
	v_cmp_eq_u32_e64 s[0:1], 0, v13
	v_cvt_f32_i32_e32 v13, v143
	v_cvt_f32_i32_e32 v44, v144
	v_subrev_u32_e32 v145, 62, v142
	v_subrev_u32_e32 v146, 61, v142
	v_and_b32_e32 v69, 0x7fffffff, v13
	v_and_b32_e32 v71, 0x7fffffff, v44
	v_cvt_f32_i32_e32 v13, v145
	v_cvt_f32_i32_e32 v44, v146
	v_subrev_u32_e32 v147, 48, v142
	v_subrev_u32_e32 v148, 47, v142
	v_subrev_u32_e32 v149, 46, v142
	v_subrev_u32_e32 v150, 45, v142
	v_and_b32_e32 v73, 0x7fffffff, v13
	v_and_b32_e32 v75, 0x7fffffff, v44
	v_cvt_f32_i32_e32 v13, v147
	v_cvt_f32_i32_e32 v44, v148
	v_cvt_f32_i32_e32 v45, v149
	v_cvt_f32_i32_e32 v46, v150
	v_subrev_u32_e32 v151, 32, v142
	v_subrev_u32_e32 v152, 31, v142
	v_subrev_u32_e32 v153, 30, v142
	v_subrev_u32_e32 v154, 29, v142
	v_and_b32_e32 v77, 0x7fffffff, v13
	v_and_b32_e32 v79, 0x7fffffff, v44
	v_and_b32_e32 v81, 0x7fffffff, v45
	v_and_b32_e32 v83, 0x7fffffff, v46
	v_cvt_f32_i32_e32 v13, v151
	v_cvt_f32_i32_e32 v44, v152
	v_cvt_f32_i32_e32 v45, v153
	v_cvt_f32_i32_e32 v46, v154
	v_add_u32_e32 v155, -16, v142
	v_add_u32_e32 v156, -15, v142
	v_add_u32_e32 v157, -14, v142
	v_add_u32_e32 v158, -13, v142
	v_and_b32_e32 v85, 0x7fffffff, v13
	v_and_b32_e32 v87, 0x7fffffff, v44
	v_and_b32_e32 v89, 0x7fffffff, v45
	v_and_b32_e32 v91, 0x7fffffff, v46
	v_cvt_f32_i32_e32 v13, v155
	v_cvt_f32_i32_e32 v44, v156
	v_cvt_f32_i32_e32 v45, v157
	v_cvt_f32_i32_e32 v46, v158
	v_add_u32_e32 v159, 1, v142
	v_add_u32_e32 v160, 2, v142
	v_add_u32_e32 v161, 3, v142
	v_and_b32_e32 v93, 0x7fffffff, v13
	v_and_b32_e32 v95, 0x7fffffff, v44
	v_and_b32_e32 v97, 0x7fffffff, v45
	v_and_b32_e32 v99, 0x7fffffff, v46
	v_cvt_f32_i32_e32 v13, v142
	v_cvt_f32_i32_e32 v44, v159
	v_cvt_f32_i32_e32 v45, v160
	v_cvt_f32_i32_e32 v46, v161
	v_add_u32_e32 v162, 16, v142
	v_add_u32_e32 v163, 17, v142
	v_add_u32_e32 v164, 18, v142
	v_add_u32_e32 v165, 19, v142
	v_add_u32_e32 v166, 32, v142
	v_add_u32_e32 v167, 33, v142
	v_add_u32_e32 v168, 34, v142
	v_add_u32_e32 v169, 35, v142
	v_add_u32_e32 v170, 48, v142
	v_add_u32_e32 v171, 49, v142
	v_add_u32_e32 v172, 50, v142
	v_add_u32_e32 v173, 51, v142
	v_add_u32_e32 v174, 64, v142
	v_add_u32_e32 v175, 0x41, v142
	v_add_u32_e32 v176, 0x42, v142
	v_add_u32_e32 v177, 0x43, v142
	v_readlane_b32 s4, v253, 8
	v_or3_b32 v12, v12, v141, v67
	v_cvt_f32_u32_e32 v109, v162
	v_cvt_f32_u32_e32 v111, v163
	v_cvt_f32_u32_e32 v113, v164
	v_cvt_f32_u32_e32 v115, v165
	v_cvt_f32_u32_e32 v117, v166
	v_cvt_f32_u32_e32 v119, v167
	v_cvt_f32_u32_e32 v121, v168
	v_cvt_f32_u32_e32 v123, v169
	v_cvt_f32_u32_e32 v125, v170
	v_cvt_f32_u32_e32 v127, v171
	v_cvt_f32_u32_e32 v129, v172
	v_cvt_f32_u32_e32 v131, v173
	v_cvt_f32_u32_e32 v133, v174
	v_cvt_f32_u32_e32 v135, v175
	v_cvt_f32_u32_e32 v137, v176
	v_cvt_f32_u32_e32 v178, v177
	v_readlane_b32 s6, v253, 10
	v_and_b32_e32 v14, 24, v14
	v_mul_lo_u32 v12, v12, s33
	v_readlane_b32 s5, v253, 9
	v_readlane_b32 s7, v253, 11
	s_add_u32 s40, s6, 0x2eb00000
	v_add3_u32 v179, 0, v14, v12
	s_mov_b32 s44, 0x3e38aa3b
	v_mov_b32_e32 v136, 0x3e38aa3b
	v_mbcnt_lo_u32_b32 v12, -1, 0
	s_addc_u32 s41, s7, 0
	s_mov_b32 s43, 0
	v_cmp_lt_i32_e64 s[24:25], -1, v142
	v_cmp_lt_i32_e64 s[4:5], -2, v142
	v_cmp_lt_i32_e64 s[6:7], -3, v142
	v_cmp_lt_i32_e64 s[8:9], -4, v142
	v_and_b32_e32 v101, 0x7fffffff, v13
	v_and_b32_e32 v103, 0x7fffffff, v44
	v_and_b32_e32 v105, 0x7fffffff, v45
	v_and_b32_e32 v107, 0x7fffffff, v46
	v_cmp_gt_i32_e64 s[10:11], 1, v142
	v_cmp_gt_i32_e64 s[12:13], 0, v142
	v_cmp_gt_i32_e64 s[14:15], -1, v142
	v_cmp_gt_i32_e64 s[16:17], -2, v142
	v_add_u32_e32 v180, 0xd800, v179
	s_mov_b32 s45, 0x3fb8aa3b
	v_mov_b32_e32 v134, v136
	v_mov_b32_e32 v132, v136
	v_mov_b32_e32 v130, v136
	v_mov_b32_e32 v128, v136
	v_mov_b32_e32 v126, v136
	v_mov_b32_e32 v124, v136
	v_mov_b32_e32 v122, v136
	v_mov_b32_e32 v120, v136
	v_mov_b32_e32 v118, v136
	v_mov_b32_e32 v116, v136
	v_mov_b32_e32 v114, v136
	v_mov_b32_e32 v112, v136
	v_mov_b32_e32 v110, v136
	v_mov_b32_e32 v108, v136
	v_mov_b32_e32 v106, v136
	v_mov_b32_e32 v104, v136
	v_mov_b32_e32 v102, v136
	v_mov_b32_e32 v100, v136
	v_mov_b32_e32 v98, v136
	v_mov_b32_e32 v96, v136
	v_mov_b32_e32 v94, v136
	v_mov_b32_e32 v92, v136
	v_mov_b32_e32 v90, v136
	v_mov_b32_e32 v88, v136
	v_mov_b32_e32 v86, v136
	v_mov_b32_e32 v84, v136
	v_mov_b32_e32 v82, v136
	v_mov_b32_e32 v80, v136
	v_mov_b32_e32 v78, v136
	v_mov_b32_e32 v76, v136
	v_mov_b32_e32 v74, v136
	v_mov_b32_e32 v72, v136
	v_mov_b32_e32 v70, v136
	v_mov_b32_e32 v68, v136
	s_lshl_b32 s48, s99, 7
	s_lshl_b32 s49, s93, 7
	s_movk_i32 s50, 0x800
	s_mov_b32 s51, 0x42fc0000
	s_mov_b32 s52, 0xf149f2ca
	v_lshlrev_b32_e32 v138, 1, v66
	s_mov_b32 s53, 0x800000
	s_mov_b32 s54, 0x3f317217
	s_mov_b32 s55, 0x7f800000
	v_mov_b32_e32 v44, 0
	v_mov_b32_e32 v181, 0x42800000
	v_mov_b32_e32 v182, 0xf149f2ca
	v_mbcnt_hi_u32_b32 v183, -1, v12
	v_mov_b32_e32 v184, 0x41b17218
	v_mov_b32_e32 v185, 0x14000
	s_mov_b32 s23, s99
	s_waitcnt vmcnt(0)
	s_branch .LBB0_720

; __device__ void phase_attn(const Params& p, unsigned char* smem, int wave) {
;     ...
;     if ((int)blockIdx.x < npairs) { ATT_DECODE(blockIdx.x) ATT_LOAD(); }
;     for (int pr = blockIdx.x; pr < npairs; pr += gridDim.x) {
;         ATT_DECODE(pr)
;         bf16_t* ato = (bf16_t*)(p.ws + (br < 2 ? WS_RA + br * ATO_STRIDE_01 : WS_ATO2));
;         __syncthreads();
;         const int hs = fresh_tid(wave);
; #pragma unroll
;         for (int c_ = 0; c_ < 2; ++c_) { const int e = hs + 512 * c_; *(u32x4*)(Qs + (e >> 3) * ATT_LD + (e & 7) * 8) = qr[c_]; }
; #pragma unroll
;         for (int c_ = 0; c_ < 4; ++c_) { const int e = hs + 512 * c_; *(u32x4*)(Ks + (e >> 3) * ATT_LD + (e & 7) * 8) = kr[c_]; *(u32x4*)(Vs + (e >> 3) * ATT_LD + (e & 7) * 8) = vr[c_]; }
;         __syncthreads();
;         if (pr + (int)gridDim.x < npairs) { ATT_DECODE(pr + gridDim.x) ATT_LOAD(); }
.LBB0_722:
	s_waitcnt lgkmcnt(0)
	s_barrier
	v_mbcnt_lo_u32_b32 v12, -1, 0
	v_mbcnt_hi_u32_b32 v12, -1, v12
	s_add_i32 s56, s23, s93
	v_or_b32_e32 v13, s70, v12
	v_lshlrev_b32_e32 v12, 4, v12
	v_and_b32_e32 v12, 0x70, v12
	v_add_u32_e32 v12, 0, v12
	v_lshrrev_b32_e32 v14, 3, v13
	v_mad_u64_u32 v[46:47], s[18:19], v14, s33, v[12:13]
	v_add_u32_e32 v14, 0x200, v13
	v_lshrrev_b32_e32 v14, 3, v14
	v_mad_u64_u32 v[48:49], s[18:19], v14, s33, v[12:13]
	v_add_u32_e32 v14, 0x400, v13
	v_lshrrev_b32_e32 v14, 3, v14
	s_waitcnt vmcnt(18)
	ds_write_b128 v46, v[0:3]
	s_waitcnt vmcnt(17)
	ds_write_b128 v48, v[4:7]
	ds_write_b128 v46, v[16:19] offset:18432
	ds_write_b128 v46, v[20:23] offset:55296
	ds_write_b128 v48, v[8:11] offset:18432
	ds_write_b128 v48, v[24:27] offset:55296
	v_mad_u64_u32 v[46:47], s[18:19], v14, s33, v[12:13]
	v_add_u32_e32 v13, 0x600, v13
	s_cmpk_gt_i32 s56, 0x3bff
	v_lshrrev_b32_e32 v13, 3, v13
	s_cselect_b64 s[46:47], -1, 0
	v_mad_u64_u32 v[12:13], s[18:19], v13, s33, v[12:13]
	s_and_b64 vcc, exec, s[46:47]
	ds_write_b128 v46, v[28:31] offset:18432
	ds_write_b128 v46, v[32:35] offset:55296
	ds_write_b128 v12, v[36:39] offset:18432
	ds_write_b128 v12, v[40:43] offset:55296
	s_waitcnt lgkmcnt(0)
	s_barrier
	s_cbranch_vccnz .LBB0_732
	s_mul_hi_i32 s18, s56, 0x66666667
	s_lshr_b32 s19, s18, 31
	s_ashr_i32 s18, s18, 8
	s_add_i32 s18, s18, s19
	s_mul_i32 s19, s18, 0xfffffd80
	s_mul_i32 s27, s18, 0xfffec000
	s_add_i32 s28, s49, s48
	s_add_i32 s19, s56, s19
	s_add_i32 s28, s28, s27
	s_and_b32 s26, s18, -8
	s_and_b32 s27, s28, 0xfffff800
	s_and_b32 s28, s19, 15
	s_add_i32 s29, s19, 0xfffffe00
	s_cmp_eq_u32 s26, 8
	s_cselect_b32 s26, 2, 4
	s_cselect_b32 s30, 3, 15
	s_cmp_lt_u32 s18, 8
	s_cselect_b32 s26, 0, s26
	s_cselect_b32 s30, 0, s30
	s_cmpk_lt_i32 s19, 0x200
	s_cselect_b32 s19, s28, s29
	s_cselect_b32 s27, s27, 0x10000
	s_cselect_b32 s28, s50, 0x4000
	s_and_b32 s29, s30, s19
	s_lshr_b32 s19, s19, s26
	v_mbcnt_lo_u32_b32 v0, -1, 0
	v_mbcnt_hi_u32_b32 v0, -1, v0
	s_lshl_b32 s18, s18, 6
	v_or_b32_e32 v13, s70, v0
	s_lshl_b32 s19, s19, 7
	s_and_b32 s18, s18, 0x1c0
	v_lshlrev_b32_e32 v0, 3, v0
	v_ashrrev_i32_e32 v8, 3, v13
	v_add_u32_e32 v2, 0x200, v13
	v_and_or_b32 v12, v0, 56, s18
	v_add_u32_e32 v0, s19, v8
	v_ashrrev_i32_e32 v24, 3, v2
	s_or_b32 s27, s29, s27
	v_lshlrev_b32_e32 v0, s26, v0
	v_add_u32_e32 v2, s19, v24
	v_add_u32_e32 v0, s27, v0
	v_lshlrev_b32_e32 v2, s26, v2
	v_mul_lo_u32 v0, v0, s3
	v_add_u32_e32 v2, s27, v2
	v_or_b32_e32 v14, v0, v12
	v_mul_lo_u32 v2, v2, s3
	v_lshl_add_u64 v[0:1], v[14:15], 1, s[38:39]
	v_or_b32_e32 v14, v2, v12
	v_lshl_add_u64 v[4:5], v[14:15], 1, s[38:39]
	global_load_dwordx4 v[0:3], v[0:1], off
	s_nop 0
	global_load_dwordx4 v[4:7], v[4:5], off
	s_sub_i32 s29, s19, 64
	s_lshr_b32 s28, s28, s26
	v_add_u32_e32 v14, s29, v8
	v_mov_b32_e32 v10, v44
	v_mov_b32_e32 v11, v44
	v_cmp_lt_i32_e32 vcc, -1, v14
	v_cmp_gt_i32_e64 s[18:19], s28, v14
	v_mov_b32_e32 v8, 0
	v_mov_b32_e32 v9, v44
	v_mov_b64_e32 v[18:19], v[10:11]
	v_mov_b64_e32 v[22:23], v[10:11]
	s_and_b64 s[30:31], vcc, s[18:19]
	v_mov_b64_e32 v[16:17], v[8:9]
	v_mov_b64_e32 v[20:21], v[8:9]
	s_and_saveexec_b64 s[18:19], s[30:31]
	s_cbranch_execz .LBB0_725
	v_lshlrev_b32_e32 v14, s26, v14
	v_add_u32_e32 v14, s27, v14
	v_mul_lo_u32 v14, v14, s3
	v_or_b32_e32 v14, v14, v12
	v_lshl_add_u64 v[20:21], v[14:15], 1, s[38:39]
	global_load_dwordx4 v[16:19], v[20:21], off offset:1024
	s_nop 0
	global_load_dwordx4 v[20:23], v[20:21], off offset:2048

; __device__ void phase_mixin(const Params& p, unsigned char* smem, int wave) {
;     const int tid = fresh_tid(wave);
;     bf16_t* tl = (bf16_t*)smem;
;     const bf16_t* hy = (const bf16_t*)(p.ws + WS_RE);
;     const float* lse = (const float*)(p.ws + WS_LSE);
;     bf16_t* mix = (bf16_t*)(p.ws + WS_RC);
;     for (int it = blockIdx.x; it < NTOK / 64; it += gridDim.x) {
;         const int g0 = it * 64;
;         const int tt = tid >> 3, sub = tid & 7, g = g0 + tt;
;         u32x4 tv[8], av[8], bv[8], cv[8];
;         { const bf16_t* src = hy + (size_t)tid * NTOK + g0;
; #pragma unroll
;           for (int q = 0; q < 8; ++q) tv[q] = *(const u32x4*)(src + 8 * q); }
;         const int h = sub;
;         const float l0 = lse[((size_t)0 * NTOK + g) * 8 + h], l1 = lse[((size_t)1 * NTOK + g) * 8 + h], l2 = lse[((size_t)2 * NTOK + g) * 8 + h];
;         { const bf16_t* o0 = (const bf16_t*)(p.ws + WS_RA) + (size_t)g * 512 + h * 64;
;           const bf16_t* o1 = (const bf16_t*)(p.ws + WS_RA + ATO_STRIDE_01) + (size_t)g * 512 + h * 64;
;           const bf16_t* o2 = (const bf16_t*)(p.ws + WS_ATO2) + (size_t)g * 512 + h * 64;
; #pragma unroll
;           for (int q = 0; q < 8; ++q) { av[q] = *(const u32x4*)(o0 + 8 * q); bv[q] = *(const u32x4*)(o1 + 8 * q); cv[q] = *(const u32x4*)(o2 + 8 * q); } }
.LBB0_744:
	s_cmp_lt_i32 s72, 7
	s_cselect_b64 s[0:1], -1, 0
	s_and_b64 s[4:5], s[0:1], s[4:5]
	s_andn2_b64 vcc, exec, s[4:5]
	s_cbranch_vccnz .LBB0_748
	s_cmpk_gt_i32 s2, 0x4ff
	s_waitcnt vmcnt(0)
	v_mbcnt_lo_u32_b32 v0, -1, 0
	v_mbcnt_hi_u32_b32 v0, -1, v0
	s_cbranch_scc1 .LBB0_748
	v_readlane_b32 s8, v253, 8
	v_readlane_b32 s10, v253, 10
	v_readlane_b32 s11, v253, 11
	v_or_b32_e32 v1, s70, v0
	s_mov_b32 s3, 0x28000
	v_mov_b64_e32 v[2:3], s[10:11]
	v_mad_i64_i32 v[2:3], s[6:7], v1, s3, v[2:3]
	s_mov_b64 s[6:7], 0x24b00000
	s_nop 0
	v_lshl_add_u64 v[104:105], v[2:3], 0, s[6:7]
	v_mbcnt_lo_u32_b32 v2, -1, 0
	v_mbcnt_hi_u32_b32 v2, -1, v2
	v_and_b32_e32 v5, 64, v2
	v_xor_b32_e32 v3, 1, v2
	v_add_u32_e32 v5, 64, v5
	v_cmp_lt_i32_e32 vcc, v3, v5
	v_and_b32_e32 v0, 7, v0
	s_movk_i32 s3, 0x84
	v_cndmask_b32_e32 v3, v2, v3, vcc
	v_lshlrev_b32_e32 v176, 2, v3
	v_xor_b32_e32 v3, 2, v2
	v_cmp_lt_i32_e32 vcc, v3, v5
	v_readlane_b32 s9, v253, 9
	s_add_u32 s4, s10, 0x2eb00000
	v_cndmask_b32_e32 v3, v2, v3, vcc
	v_lshlrev_b32_e32 v177, 2, v3
	v_xor_b32_e32 v3, 4, v2
	v_cmp_lt_i32_e32 vcc, v3, v5
	v_ashrrev_i32_e32 v121, 3, v1
	v_mov_b32_e32 v107, 0
	v_cndmask_b32_e32 v2, v2, v3, vcc
	v_lshlrev_b32_e32 v178, 2, v2
	v_lshl_or_b32 v2, v0, 6, 2
	v_mov_b32_e32 v3, 0xf78
	v_mad_u32_u24 v6, v2, s3, v3
	v_mov_b32_e32 v3, 0x420
	v_lshlrev_b32_e32 v106, 7, v0
	s_addc_u32 s5, s11, 0
	v_lshl_add_u32 v4, v121, 1, 0
	s_movk_i32 s6, 0x2100
	v_mul_u32_u24_e32 v5, 0x84, v2
	v_mad_u32_u24 v7, v2, s3, v3
	v_lshl_add_u64 v[2:3], s[10:11], 0, v[106:107]
	v_readlane_b32 s8, v253, 44
	v_mad_u32_u24 v179, v0, s6, v4
	s_mov_b64 s[6:7], 0x37b00000
	v_readlane_b32 s9, v253, 45
	v_readlane_b32 s10, v253, 46
	v_readlane_b32 s11, v253, 47
	v_readlane_b32 s12, v253, 48
	v_readlane_b32 s13, v253, 49
	v_lshl_add_u64 v[110:111], v[2:3], 0, s[6:7]
	s_mov_b64 s[6:7], 0x29b00000
	v_readlane_b32 s14, v253, 50
	v_readlane_b32 s15, v253, 51
	s_mov_b64 s[8:9], s[12:13]
	v_mul_lo_u32 v1, v1, s3
	v_lshl_add_u64 v[108:109], s[66:67], 0, v[106:107]
	v_lshl_add_u64 v[112:113], v[2:3], 0, s[6:7]
	v_lshlrev_b32_e32 v106, 8, v0
	s_mov_b64 s[10:11], s[14:15]
	s_mov_b64 s[6:7], 0x1b00000
	v_lshl_add_u64 v[114:115], s[8:9], 0, v[106:107]
	v_lshl_add_u64 v[116:117], s[10:11], 0, v[106:107]
	v_mbcnt_lo_u32_b32 v232, -1, 0
	v_mbcnt_hi_u32_b32 v232, -1, v232
	v_lshlrev_b32_e32 v233, 2, v232
	s_lshr_b32 s24, s70, 6
	s_mul_i32 s24, s24, 0x110
	s_add_i32 s24, s24, 0x11000
	v_add_u32_e32 v234, s24, v233
	s_lshl_b32 s25, s70, 2
	v_add_u32_e32 v233, s25, v233
	global_load_dword v235, v233, s[8:9]
	global_load_dword v236, v233, s[10:11]
	v_lshrrev_b32_e32 v230, 4, v106
	s_mov_b32 s25, 0x11000
	v_add3_u32 v230, v230, v106, s25
	s_waitcnt vmcnt(0)
	ds_write_b32 v234, v235
	ds_write_b32 v234, v236 offset:2176
	s_waitcnt lgkmcnt(0)
	s_barrier
	v_lshl_add_u64 v[118:119], v[2:3], 0, s[6:7]
	s_lshl_b32 s6, s2, 6
	s_lshl_b32 s9, s93, 6
	v_lshlrev_b32_e32 v106, 2, v0
	s_mov_b32 s10, 0x280000
	s_mov_b32 s11, 0x500000
	v_add_u32_e32 v180, 0, v1
	v_add_u32_e32 v181, v4, v5
	v_add_u32_e32 v182, v4, v6
	v_add_u32_e32 v183, v4, v7
	s_mov_b32 s8, 0x3b000000
	s_mov_b32 s12, 0x800000
	v_mov_b32_e32 v120, 0x358637bd
	s_mov_b32 s13, s2
	v_readlane_b32 s16, v253, 52
	v_readlane_b32 s17, v253, 53
	v_readlane_b32 s18, v253, 54
	v_readlane_b32 s19, v253, 55
	v_readlane_b32 s20, v253, 56
	v_readlane_b32 s21, v253, 57
	v_readlane_b32 s22, v253, 58
	v_readlane_b32 s23, v253, 59
.LBB0_747:
	s_ashr_i32 s7, s6, 31
	v_lshl_add_u64 v[0:1], s[6:7], 1, v[104:105]
	global_load_dwordx4 v[96:99], v[0:1], off
	global_load_dwordx4 v[100:103], v[0:1], off offset:16
	global_load_dwordx4 v[134:137], v[0:1], off offset:32
	global_load_dwordx4 v[138:141], v[0:1], off offset:48
	global_load_dwordx4 v[142:145], v[0:1], off offset:64
	global_load_dwordx4 v[146:149], v[0:1], off offset:80
	global_load_dwordx4 v[150:153], v[0:1], off offset:96
	global_load_dwordx4 v[154:157], v[0:1], off offset:112
	v_add_u32_e32 v122, s6, v121
	v_ashrrev_i32_e32 v123, 31, v122
	v_lshlrev_b64 v[0:1], 5, v[122:123]
	v_lshlrev_b64 v[2:3], 10, v[122:123]
	v_lshl_add_u64 v[0:1], s[4:5], 0, v[0:1]
	v_lshl_add_u64 v[80:81], v[108:109], 0, v[2:3]
	v_lshl_add_u64 v[8:9], v[110:111], 0, v[2:3]
	v_lshl_add_u64 v[82:83], v[112:113], 0, v[2:3]
	v_lshl_add_u64 v[124:125], v[0:1], 0, v[106:107]
	global_load_dwordx4 v[48:51], v[80:81], off offset:32
	global_load_dwordx4 v[60:63], v[80:81], off offset:16
	global_load_dwordx4 v[52:55], v[8:9], off offset:32
	global_load_dwordx4 v[64:67], v[8:9], off offset:16
	global_load_dwordx4 v[56:59], v[82:83], off offset:32
	global_load_dwordx4 v[68:71], v[82:83], off offset:16
	global_load_dwordx4 v[0:3], v[80:81], off offset:96
	global_load_dwordx4 v[12:15], v[80:81], off offset:80
	global_load_dwordx4 v[36:39], v[80:81], off offset:48
	global_load_dwordx4 v[24:27], v[80:81], off offset:64
	global_load_dwordx4 v[72:75], v[8:9], off
	global_load_dwordx4 v[84:87], v[80:81], off offset:112
	global_load_dwordx4 v[4:7], v[8:9], off offset:96
	global_load_dwordx4 v[16:19], v[8:9], off offset:80
	global_load_dwordx4 v[40:43], v[8:9], off offset:48
	global_load_dwordx4 v[28:31], v[8:9], off offset:64
	global_load_dwordx4 v[76:79], v[82:83], off
	global_load_dwordx4 v[88:91], v[8:9], off offset:112
	s_nop 0
	global_load_dwordx4 v[8:11], v[82:83], off offset:96
	global_load_dwordx4 v[20:23], v[82:83], off offset:80
	global_load_dwordx4 v[44:47], v[82:83], off offset:48
	global_load_dwordx4 v[32:35], v[82:83], off offset:64
	global_load_dwordx4 v[92:95], v[82:83], off offset:112
	v_add_co_u32_e32 v82, vcc, s10, v124
	s_add_i32 s13, s13, s93
	s_nop 0
	v_addc_co_u32_e32 v83, vcc, 0, v125, vcc
	v_add_co_u32_e32 v126, vcc, s11, v124
	s_add_i32 s6, s6, s9
	s_nop 0
	v_addc_co_u32_e32 v127, vcc, 0, v125, vcc
	global_load_dword v132, v[124:125], off
	global_load_dword v128, v[82:83], off
	s_nop 0
	global_load_dword v124, v[126:127], off
	s_nop 0
	global_load_dwordx4 v[80:83], v[80:81], off
	s_waitcnt lgkmcnt(0)
	s_barrier
; __device__ __forceinline__ float bf2f(bf16_t b) { return __uint_as_float(((unsigned)b) << 16); }
; __device__ void phase_mixin(const Params& p, unsigned char* smem, int wave) {
;     ...
;         __syncthreads();
; #pragma unroll
;         for (int q = 0; q < 8; ++q) { unsigned* dst = (unsigned*)(tl + tid * 66 + 8 * q); dst[0] = tv[q].x; dst[1] = tv[q].y; dst[2] = tv[q].z; dst[3] = tv[q].w; }
;         __syncthreads();
;         { float ss = 0.f;
;           for (int c = sub * 64; c < sub * 64 + 64; ++c) { const float v = bf2f(tl[c * 66 + tt]); ss += v * v; }
	s_cmpk_lt_i32 s13, 0x500
	s_waitcnt vmcnt(34)
	ds_write2_b32 v180, v96, v97 offset1:1
	ds_write2_b32 v180, v98, v99 offset0:2 offset1:3
	s_waitcnt vmcnt(33)
	ds_write2_b32 v180, v100, v101 offset0:4 offset1:5
	ds_write2_b32 v180, v102, v103 offset0:6 offset1:7
	s_waitcnt vmcnt(32)
	ds_write2_b32 v180, v134, v135 offset0:8 offset1:9
	ds_write2_b32 v180, v136, v137 offset0:10 offset1:11
	s_waitcnt vmcnt(31)
	ds_write2_b32 v180, v138, v139 offset0:12 offset1:13
	ds_write2_b32 v180, v140, v141 offset0:14 offset1:15
	s_waitcnt vmcnt(30)
	ds_write2_b32 v180, v142, v143 offset0:16 offset1:17
	ds_write2_b32 v180, v144, v145 offset0:18 offset1:19
	s_waitcnt vmcnt(29)
	ds_write2_b32 v180, v146, v147 offset0:20 offset1:21
	ds_write2_b32 v180, v148, v149 offset0:22 offset1:23
	s_waitcnt vmcnt(28)
	ds_write2_b32 v180, v150, v151 offset0:24 offset1:25
	ds_write2_b32 v180, v152, v153 offset0:26 offset1:27
	s_waitcnt vmcnt(27)
	ds_write2_b32 v180, v154, v155 offset0:28 offset1:29
	ds_write2_b32 v180, v156, v157 offset0:30 offset1:31
	s_waitcnt lgkmcnt(0)
	s_barrier
	ds_read_u16 v97, v179 offset:1188
	ds_read_u16 v98, v179 offset:1320
	ds_read_u16 v99, v179 offset:1452
	ds_read_u16 v96, v179 offset:924
	s_waitcnt lgkmcnt(3)
	v_lshlrev_b32_e32 v135, 16, v97
	s_waitcnt lgkmcnt(2)
	v_lshlrev_b32_e32 v126, 16, v98
	s_waitcnt lgkmcnt(1)
	v_lshlrev_b32_e32 v133, 16, v99
	ds_read_u16 v97, v179 offset:1584
	ds_read_u16 v98, v179 offset:1716
	ds_read_u16 v99, v179 offset:1848
	ds_read_u16 v100, v179 offset:1980
	ds_read_u16 v101, v179 offset:2244
	ds_read_u16 v102, v179 offset:2376
	ds_read_u16 v103, v179 offset:2508
	ds_read_u16 v125, v179 offset:2640
	s_waitcnt lgkmcnt(7)
	v_lshlrev_b32_e32 v130, 16, v97
	s_waitcnt lgkmcnt(6)
	v_lshlrev_b32_e32 v143, 16, v98
	s_waitcnt lgkmcnt(5)
	v_lshlrev_b32_e32 v140, 16, v99
	s_waitcnt lgkmcnt(4)
	v_lshlrev_b32_e32 v141, 16, v100
	s_waitcnt lgkmcnt(3)
	v_lshlrev_b32_e32 v131, 16, v101
	s_waitcnt lgkmcnt(2)
	v_lshlrev_b32_e32 v136, 16, v102
	s_waitcnt lgkmcnt(1)
	v_lshlrev_b32_e32 v129, 16, v103
	ds_read_u16 v97, v179 offset:2772
	ds_read_u16 v98, v179 offset:2904
	ds_read_u16 v99, v179 offset:3036
	ds_read_u16 v100, v179 offset:3300
	ds_read_u16 v101, v179 offset:3432
	ds_read_u16 v102, v179 offset:3564
	ds_read_u16 v103, v179 offset:3696
	ds_read_u16 v134, v179 offset:3828
	s_waitcnt lgkmcnt(8)
	v_lshlrev_b32_e32 v138, 16, v125
	s_waitcnt lgkmcnt(7)
	v_lshlrev_b32_e32 v139, 16, v97
	s_waitcnt lgkmcnt(6)
	v_lshlrev_b32_e32 v148, 16, v98
	s_waitcnt lgkmcnt(5)
	v_lshlrev_b32_e32 v137, 16, v99
	s_waitcnt lgkmcnt(4)
	v_lshlrev_b32_e32 v127, 16, v100
	s_waitcnt lgkmcnt(3)
	v_lshlrev_b32_e32 v142, 16, v101
	s_waitcnt lgkmcnt(2)
	v_lshlrev_b32_e32 v125, 16, v102
	ds_read_u16 v97, v182
	ds_read_u16 v101, v179 offset:3960
	ds_read_u16 v102, v179 offset:4092
	ds_read_u16 v98, v179 offset:4356
	ds_read_u16 v99, v179 offset:4488
	ds_read_u16 v100, v179 offset:4620
	ds_read_u16 v184, v179 offset:4356
	ds_read_u16 v186, v179 offset:4092
	ds_read_u16 v187, v179 offset:3828
	s_waitcnt lgkmcnt(7)
	v_lshlrev_b32_e32 v149, 16, v101
	ds_read_u16 v185, v182 offset:264
	ds_read_u16 v213, v181 offset:2904
	v_lshlrev_b32_e32 v144, 16, v97
	s_waitcnt lgkmcnt(7)
	v_lshlrev_b32_e32 v218, 16, v98
	s_waitcnt lgkmcnt(6)
	v_lshlrev_b32_e32 v219, 16, v99
	s_waitcnt lgkmcnt(5)
	v_lshlrev_b32_e32 v220, 16, v100
	ds_read_u16 v97, v179 offset:4752
	ds_read_u16 v98, v179 offset:4884
	ds_read_u16 v99, v179 offset:5016
	ds_read_u16 v100, v179 offset:5148
	ds_read_u16 v101, v179 offset:5412
	ds_read_u16 v188, v179 offset:5148
	ds_read_u16 v189, v179 offset:4884
	ds_read_u16 v190, v179 offset:4620
	s_waitcnt lgkmcnt(7)
	v_lshlrev_b32_e32 v221, 16, v97
	ds_read_u16 v97, v182 offset:1056
	ds_read_u16 v225, v182 offset:2112
	ds_read_u16 v191, v182 offset:1320
	ds_read_u16 v192, v182 offset:1584
	ds_read_u16 v193, v182 offset:2376
	ds_read_u16 v194, v182 offset:1848
	ds_read_u16 v199, v182 offset:792
	s_waitcnt lgkmcnt(13)
	v_lshlrev_b32_e32 v222, 16, v98
	s_waitcnt lgkmcnt(11)
	v_lshlrev_b32_e32 v224, 16, v100
	s_waitcnt lgkmcnt(6)
	v_lshlrev_b32_e32 v146, 16, v97
	ds_read_u16 v97, v179 offset:5676
	ds_read_u16 v98, v179 offset:5544
	ds_read_u16 v100, v179 offset:5940
	ds_read_u16 v196, v179 offset:5940
	ds_read_u16 v198, v179 offset:5676
	v_lshlrev_b32_e32 v223, 16, v99
	v_lshlrev_b32_e32 v226, 16, v101
	s_waitcnt lgkmcnt(4)
	v_lshlrev_b32_e32 v99, 16, v97
	ds_read_u16 v97, v179 offset:5808
	ds_read_u16 v101, v179 offset:6072
	ds_read_u16 v200, v179 offset:5412
	s_waitcnt lgkmcnt(6)
	v_lshlrev_b32_e32 v98, 16, v98
	v_pk_mul_f32 v[150:151], v[98:99], v[98:99]
	s_waitcnt lgkmcnt(5)
	v_lshlrev_b32_e32 v99, 16, v100
	s_waitcnt lgkmcnt(2)
	v_lshlrev_b32_e32 v98, 16, v97
	v_lshlrev_b32_e32 v145, 16, v103
	v_lshlrev_b32_e32 v154, 16, v102
	v_pk_mul_f32 v[152:153], v[98:99], v[98:99]
	ds_read_u16 v97, v179 offset:6204
	ds_read_u16 v100, v179 offset:6600
	ds_read_u16 v102, v179 offset:6732
	ds_read_u16 v103, v179 offset:6864
	ds_read_u16 v227, v179 offset:6468
	ds_read_u16 v195, v179 offset:6732
	ds_read_u16 v197, v179 offset:6468
	ds_read_u16 v201, v179 offset:6204
	s_waitcnt lgkmcnt(7)
	v_lshlrev_b32_e32 v99, 16, v97
	v_lshlrev_b32_e32 v98, 16, v101
	v_pk_mul_f32 v[170:171], v[98:99], v[98:99]
	s_waitcnt lgkmcnt(5)
	v_lshlrev_b32_e32 v99, 16, v102
	v_lshlrev_b32_e32 v98, 16, v100
	ds_read_u16 v97, v179 offset:6996
	ds_read_u16 v100, v179 offset:7128
	ds_read_u16 v101, v179 offset:7260
	ds_read_u16 v102, v179 offset:7656
	ds_read_u16 v228, v179 offset:7524
	ds_read_u16 v202, v179 offset:7524
	ds_read_u16 v203, v179 offset:7260
	ds_read_u16 v204, v179 offset:6996
	v_pk_mul_f32 v[172:173], v[98:99], v[98:99]
	s_waitcnt lgkmcnt(7)
; __device__ __forceinline__ unsigned pk2(float lo, float hi) { return cvtpk(lo, hi); }
; __device__ __forceinline__ float bf2f(bf16_t b) { return __uint_as_float(((unsigned)b) << 16); }
; __device__ void phase_mixin(const Params& p, unsigned char* smem, int wave) {
;     ...
;           for (int c = sub * 64; c < sub * 64 + 64; ++c) { const float v = bf2f(tl[c * 66 + tt]); ss += v * v; }
;           ss += __shfl_xor(ss, 1); ss += __shfl_xor(ss, 2); ss += __shfl_xor(ss, 4);
;           const float r = rsqrtf(ss * (1.f / 512.f) + EPS);
;           bf16_t* dst = mix + (size_t)g * D + sub * 64;
; #pragma unroll
;           for (int q = 0; q < 8; ++q) { float v[8];
; #pragma unroll
;               for (int j = 0; j < 8; ++j) { const int c = sub * 64 + 8 * q + j; v[j] = bf2f(tl[c * 66 + tt]) * r * p.hy_out_g[c]; }
;               u32x4 w; w.x = pk2(v[0], v[1]); w.y = pk2(v[2], v[3]); w.z = pk2(v[4], v[5]); w.w = pk2(v[6], v[7]);
;               *(u32x4*)(dst + 8 * q) = w; } }
;         { const float lm = fmaxf(l0, fmaxf(l1, l2)); float w0 = __expf(l0 - lm), w1 = __expf(l1 - lm), w2 = __expf(l2 - lm); const float wi = 1.f / (w0 + w1 + w2); w0 *= wi; w1 *= wi; w2 *= wi;
;           float ss = 0.f;
; #pragma unroll
;           for (int q = 0; q < 8; ++q) { const u32x4 a = av[q], b = bv[q], c = cv[q];
; #pragma unroll
;               for (int j = 0; j < 4; ++j) { const float lo = w0 * bf2f((bf16_t)a[j]) + w1 * bf2f((bf16_t)b[j]) + w2 * bf2f((bf16_t)c[j]);
;                   const float hi = w0 * bf2f((bf16_t)(a[j] >> 16)) + w1 * bf2f((bf16_t)(b[j] >> 16)) + w2 * bf2f((bf16_t)(c[j] >> 16)); ss += lo * lo + hi * hi; } }
	v_lshlrev_b32_e32 v99, 16, v97
	v_lshlrev_b32_e32 v98, 16, v103
	s_waitcnt lgkmcnt(5)
	v_lshlrev_b32_e32 v97, 16, v101
	v_lshlrev_b32_e32 v147, 16, v134
	v_pk_mul_f32 v[174:175], v[98:99], v[98:99]
	v_lshlrev_b32_e32 v155, 16, v100
	v_mul_f32_e32 v212, v97, v97
	ds_read_u16 v97, v179 offset:7788
	ds_read_u16 v100, v179 offset:7920
	ds_read_u16 v101, v179 offset:8052
	ds_read_u16 v103, v179 offset:8184
	ds_read_u16 v134, v179 offset:8316
	ds_read_u16 v205, v179 offset:8316
	ds_read_u16 v206, v179 offset:8052
	ds_read_u16 v207, v179 offset:7788
	s_waitcnt lgkmcnt(7)
	v_lshlrev_b32_e32 v99, 16, v97
	v_lshlrev_b32_e32 v98, 16, v102
	v_pk_mul_f32 v[168:169], v[98:99], v[98:99]
	s_waitcnt lgkmcnt(5)
	v_lshlrev_b32_e32 v99, 16, v101
	v_lshlrev_b32_e32 v98, 16, v100
	v_pk_mul_f32 v[164:165], v[98:99], v[98:99]
	s_waitcnt lgkmcnt(3)
	v_lshlrev_b32_e32 v99, 16, v134
	v_lshlrev_b32_e32 v98, 16, v103
	v_pk_mul_f32 v[162:163], v[98:99], v[98:99]
	ds_read_u16 v97, v181 offset:528
	ds_read_u16 v98, v179 offset:660
	v_lshlrev_b32_e32 v157, 16, v96
	ds_read_u16 v134, v181 offset:792
	ds_read_u16 v229, v181 offset:1848
	ds_read_u16 v96, v181 offset:264
	ds_read_u16 v160, v179 offset:396
	ds_read_u16 v166, v181
	ds_read_u16 v216, v179
	ds_read_u16 v167, v179 offset:132
	s_waitcnt lgkmcnt(7)
	v_lshlrev_b32_e32 v159, 16, v98
	s_waitcnt lgkmcnt(4)
	v_lshlrev_b32_e32 v158, 16, v96
	s_waitcnt lgkmcnt(3)
	v_lshlrev_b32_e32 v161, 16, v160
	s_waitcnt lgkmcnt(2)
	v_lshlrev_b32_e32 v160, 16, v166
	s_waitcnt lgkmcnt(0)
	v_lshlrev_b32_e32 v167, 16, v167
	v_lshlrev_b32_e32 v166, 16, v216
	v_pk_mul_f32 v[216:217], v[166:167], v[166:167]
	v_pk_mul_f32 v[214:215], v[160:161], v[160:161]
	v_add_f32_e32 v216, v216, v217
	v_add_f32_e32 v214, v216, v214
	v_pk_mul_f32 v[210:211], v[158:159], v[158:159]
	v_add_f32_e32 v214, v214, v215
	v_lshlrev_b32_e32 v156, 16, v97
	v_add_f32_e32 v210, v214, v210
	v_pk_mul_f32 v[208:209], v[156:157], v[156:157]
	v_add_f32_e32 v210, v210, v211
	v_add_f32_e32 v208, v210, v208
	v_lshlrev_b32_e32 v134, 16, v134
	v_add_f32_e32 v208, v208, v209
	v_fmac_f32_e32 v208, v134, v134
	v_fmac_f32_e32 v208, v135, v135
	v_fmac_f32_e32 v208, v126, v126
	v_fmac_f32_e32 v208, v133, v133
	v_fmac_f32_e32 v208, v130, v130
	v_fmac_f32_e32 v208, v143, v143
	v_fmac_f32_e32 v208, v140, v140
	v_fmac_f32_e32 v208, v141, v141
	v_lshlrev_b32_e32 v130, 16, v229
	v_fmac_f32_e32 v208, v130, v130
	v_fmac_f32_e32 v208, v131, v131
	v_fmac_f32_e32 v208, v136, v136
	v_fmac_f32_e32 v208, v129, v129
	v_fmac_f32_e32 v208, v138, v138
	v_fmac_f32_e32 v208, v139, v139
	v_fmac_f32_e32 v208, v148, v148
	v_fmac_f32_e32 v208, v137, v137
	v_lshlrev_b32_e32 v126, 16, v213
	v_fmac_f32_e32 v208, v126, v126
	v_fmac_f32_e32 v208, v127, v127
	v_fmac_f32_e32 v208, v142, v142
	v_fmac_f32_e32 v208, v125, v125
	v_fmac_f32_e32 v208, v145, v145
	v_fmac_f32_e32 v208, v147, v147
	v_fmac_f32_e32 v208, v149, v149
	v_fmac_f32_e32 v208, v154, v154
	v_fmac_f32_e32 v208, v144, v144
	v_fmac_f32_e32 v208, v218, v218
	v_fmac_f32_e32 v208, v219, v219
	v_fmac_f32_e32 v208, v220, v220
	v_fmac_f32_e32 v208, v221, v221
	v_fmac_f32_e32 v208, v222, v222
	v_fmac_f32_e32 v208, v223, v223
	v_fmac_f32_e32 v208, v224, v224
	v_fmac_f32_e32 v208, v146, v146
	v_fmac_f32_e32 v208, v226, v226
	v_add_f32_e32 v136, v208, v150
	v_add_f32_e32 v136, v136, v151
	v_add_f32_e32 v136, v136, v152
	v_add_f32_e32 v136, v136, v153
	v_add_f32_e32 v136, v136, v170
	v_lshlrev_b32_e32 v153, 16, v227
	v_lshlrev_b32_e32 v152, 16, v225
	s_waitcnt vmcnt(1)
	v_max3_f32 v138, v132, v128, v124
	v_add_f32_e32 v136, v136, v171
	v_pk_mul_f32 v[148:149], v[152:153], v[152:153]
	v_sub_f32_e32 v132, v132, v138
	v_sub_f32_e32 v128, v128, v138
	v_add_f32_e32 v136, v136, v148
	v_mul_f32_e32 v132, 0x3fb8aa3b, v132
	v_mul_f32_e32 v128, 0x3fb8aa3b, v128
	v_sub_f32_e32 v124, v124, v138
	v_add_f32_e32 v136, v136, v149
	v_exp_f32_e32 v149, v132
	v_exp_f32_e32 v148, v128
	v_mul_f32_e32 v124, 0x3fb8aa3b, v124
	v_exp_f32_e32 v124, v124
	v_add_f32_e32 v136, v136, v172
	v_add_f32_e32 v128, v149, v148
	v_add_f32_e32 v136, v136, v173
	v_add_f32_e32 v128, v124, v128
	v_add_f32_e32 v136, v136, v174
	v_div_scale_f32 v132, s[14:15], v128, v128, 1.0
	v_add_f32_e32 v171, v136, v175
	v_rcp_f32_e32 v136, v132
	ds_read_b128 v[96:99], v230 offset:16
	ds_read_b128 v[100:103], v230
	ds_read_u16 v138, v183 offset:264
	ds_read_u16 v140, v182 offset:3168
	ds_read_u16 v210, v182 offset:3432
	ds_read_u16 v209, v182 offset:3696
	ds_read_u16 v208, v182 offset:3960
	ds_read_u16 v211, v182 offset:2904
	s_waitcnt lgkmcnt(4)
	v_lshlrev_b32_e32 v150, 16, v140
	v_fma_f32 v140, -v132, v136, 1.0
	v_fmac_f32_e32 v136, v140, v136
	v_div_scale_f32 v140, vcc, 1.0, v128, 1.0
	v_mul_f32_e32 v142, v140, v136
	v_fma_f32 v145, -v132, v142, v140
	v_fmac_f32_e32 v142, v145, v136
	v_fma_f32 v132, -v132, v142, v140
	v_div_fmas_f32 v132, v132, v136, v142
	v_div_fixup_f32 v128, v132, v128, 1.0
	v_pk_mul_f32 v[174:175], v[148:149], v[128:129] op_sel_hi:[1,0]
	v_lshlrev_b32_e32 v217, 16, v85
	v_lshlrev_b32_e32 v216, 16, v88
	v_and_b32_e32 v223, 0xffff0000, v85
	v_and_b32_e32 v222, 0xffff0000, v88
	v_lshlrev_b32_e32 v219, 16, v89
	v_lshlrev_b32_e32 v218, 16, v84
	v_and_b32_e32 v85, 0xffff0000, v89
	v_and_b32_e32 v84, 0xffff0000, v84
	v_pk_mul_f32 v[88:89], v[174:175], v[216:217]
	v_pk_mul_f32 v[216:217], v[174:175], v[222:223]
	v_and_b32_e32 v223, 0xffff0000, v87
	v_pk_fma_f32 v[84:85], v[174:175], v[84:85], v[216:217] op_sel:[1,0,0] op_sel_hi:[0,1,1]
	v_lshlrev_b32_e32 v217, 16, v87
	v_lshlrev_b32_e32 v216, 16, v90
	v_and_b32_e32 v222, 0xffff0000, v90
	s_waitcnt vmcnt(0)
; __device__ __forceinline__ float bf2f(bf16_t b) { return __uint_as_float(((unsigned)b) << 16); }
; __device__ void phase_mixin(const Params& p, unsigned char* smem, int wave) {
;     ...
;           float ss = 0.f;
; #pragma unroll
;           for (int q = 0; q < 8; ++q) { const u32x4 a = av[q], b = bv[q], c = cv[q];
; #pragma unroll
;               for (int j = 0; j < 4; ++j) { const float lo = w0 * bf2f((bf16_t)a[j]) + w1 * bf2f((bf16_t)b[j]) + w2 * bf2f((bf16_t)c[j]);
;                   const float hi = w0 * bf2f((bf16_t)(a[j] >> 16)) + w1 * bf2f((bf16_t)(b[j] >> 16)) + w2 * bf2f((bf16_t)(c[j] >> 16)); ss += lo * lo + hi * hi; } }
	v_lshlrev_b32_e32 v214, 16, v83
	v_and_b32_e32 v215, 0xffff0000, v75
	v_pk_fma_f32 v[88:89], v[174:175], v[218:219], v[88:89] op_sel:[1,0,0] op_sel_hi:[0,1,1]
	v_lshlrev_b32_e32 v219, 16, v91
	v_lshlrev_b32_e32 v218, 16, v86
	v_and_b32_e32 v87, 0xffff0000, v91
	v_and_b32_e32 v86, 0xffff0000, v86
	v_pk_mul_f32 v[90:91], v[174:175], v[216:217]
	v_pk_mul_f32 v[216:217], v[174:175], v[222:223]
	v_lshlrev_b32_e32 v148, 16, v75
	v_and_b32_e32 v149, 0xffff0000, v83
	v_pk_mul_f32 v[214:215], v[174:175], v[214:215] op_sel:[1,0] op_sel_hi:[0,1]
	v_pk_fma_f32 v[86:87], v[174:175], v[86:87], v[216:217] op_sel:[1,0,0] op_sel_hi:[0,1,1]
	v_and_b32_e32 v217, 0xffff0000, v82
	v_lshlrev_b32_e32 v82, 16, v82
	v_and_b32_e32 v83, 0xffff0000, v74
	v_pk_fma_f32 v[148:149], v[174:175], v[148:149], v[214:215]
	v_lshlrev_b32_e32 v214, 16, v79
	v_and_b32_e32 v215, 0xffff0000, v79
	v_lshlrev_b32_e32 v216, 16, v74
	v_lshlrev_b32_e32 v74, 16, v78
	v_and_b32_e32 v75, 0xffff0000, v78
	v_pk_mul_f32 v[78:79], v[174:175], v[82:83] op_sel:[1,0] op_sel_hi:[0,1]
	v_mul_f32_e32 v124, v124, v128
	v_pk_fma_f32 v[78:79], v[174:175], v[216:217], v[78:79]
	v_lshlrev_b32_e32 v216, 16, v81
	v_pk_fma_f32 v[74:75], v[124:125], v[74:75], v[78:79] op_sel_hi:[0,1,1]
	v_mul_f32_e32 v78, v75, v75
	v_and_b32_e32 v217, 0xffff0000, v73
	v_pk_fma_f32 v[82:83], v[74:75], v[74:75], v[78:79] op_sel_hi:[1,1,0]
	v_lshlrev_b32_e32 v78, 16, v73
	v_and_b32_e32 v79, 0xffff0000, v81
	v_pk_mul_f32 v[216:217], v[174:175], v[216:217] op_sel:[1,0] op_sel_hi:[0,1]
	v_pk_fma_f32 v[90:91], v[174:175], v[218:219], v[90:91] op_sel:[1,0,0] op_sel_hi:[0,1,1]
	v_lshlrev_b32_e32 v218, 16, v77
	v_and_b32_e32 v219, 0xffff0000, v77
	v_pk_fma_f32 v[78:79], v[174:175], v[78:79], v[216:217]
	v_and_b32_e32 v81, 0xffff0000, v72
	v_pk_fma_f32 v[78:79], v[124:125], v[218:219], v[78:79] op_sel_hi:[0,1,1]
	v_and_b32_e32 v219, 0xffff0000, v80
	v_lshlrev_b32_e32 v80, 16, v80
	v_lshlrev_b32_e32 v218, 16, v72
	v_lshlrev_b32_e32 v72, 16, v76
	v_and_b32_e32 v73, 0xffff0000, v76
	v_pk_mul_f32 v[76:77], v[174:175], v[80:81] op_sel:[1,0] op_sel_hi:[0,1]
	v_pk_fma_f32 v[148:149], v[124:125], v[214:215], v[148:149] op_sel_hi:[0,1,1]
	v_pk_fma_f32 v[76:77], v[174:175], v[218:219], v[76:77]
	v_mul_f32_e32 v128, v149, v149
	v_pk_fma_f32 v[76:77], v[124:125], v[72:73], v[76:77] op_sel_hi:[0,1,1]
	v_pk_fma_f32 v[214:215], v[148:149], v[148:149], v[128:129] op_sel_hi:[1,1,0]
	v_mul_f32_e32 v128, v79, v79
	v_mul_f32_e32 v72, v77, v77
	v_pk_fma_f32 v[216:217], v[78:79], v[78:79], v[128:129] op_sel_hi:[1,1,0]
	v_pk_fma_f32 v[72:73], v[76:77], v[76:77], v[72:73] op_sel_hi:[1,1,0]
	v_lshlrev_b32_e32 v151, 16, v228
	v_pk_add_f32 v[72:73], v[72:73], v[216:217]
	v_lshlrev_b32_e32 v216, 16, v69
	v_pk_add_f32 v[72:73], v[82:83], v[72:73]
	v_lshlrev_b32_e32 v82, 16, v63
	v_and_b32_e32 v83, 0xffff0000, v67
	v_pk_add_f32 v[80:81], v[214:215], v[72:73]
	v_lshlrev_b32_e32 v72, 16, v67
	v_and_b32_e32 v73, 0xffff0000, v63
	v_pk_mul_f32 v[82:83], v[174:175], v[82:83] op_sel:[1,0] op_sel_hi:[0,1]
	v_lshlrev_b32_e32 v214, 16, v71
	v_and_b32_e32 v215, 0xffff0000, v71
	v_pk_fma_f32 v[72:73], v[174:175], v[72:73], v[82:83]
	v_and_b32_e32 v63, 0xffff0000, v66
	v_pk_fma_f32 v[72:73], v[124:125], v[214:215], v[72:73] op_sel_hi:[0,1,1]
	v_and_b32_e32 v215, 0xffff0000, v62
	v_lshlrev_b32_e32 v62, 16, v62
	v_lshlrev_b32_e32 v214, 16, v66
	v_pk_mul_f32 v[62:63], v[174:175], v[62:63] op_sel:[1,0] op_sel_hi:[0,1]
	v_lshlrev_b32_e32 v66, 16, v70
	v_and_b32_e32 v67, 0xffff0000, v70
	v_pk_fma_f32 v[62:63], v[174:175], v[214:215], v[62:63]
	v_lshlrev_b32_e32 v214, 16, v61
	v_pk_fma_f32 v[62:63], v[124:125], v[66:67], v[62:63] op_sel_hi:[0,1,1]
	v_mul_f32_e32 v66, v63, v63
	v_and_b32_e32 v215, 0xffff0000, v65
	v_pk_fma_f32 v[70:71], v[62:63], v[62:63], v[66:67] op_sel_hi:[1,1,0]
	v_lshlrev_b32_e32 v66, 16, v65
	v_and_b32_e32 v67, 0xffff0000, v61
	v_pk_mul_f32 v[214:215], v[174:175], v[214:215] op_sel:[1,0] op_sel_hi:[0,1]
	v_and_b32_e32 v217, 0xffff0000, v69
	v_pk_fma_f32 v[66:67], v[174:175], v[66:67], v[214:215]
	v_and_b32_e32 v61, 0xffff0000, v64
	v_pk_fma_f32 v[66:67], v[124:125], v[216:217], v[66:67] op_sel_hi:[0,1,1]
	v_and_b32_e32 v217, 0xffff0000, v60
	v_lshlrev_b32_e32 v60, 16, v60
	v_lshlrev_b32_e32 v216, 16, v64
	v_pk_mul_f32 v[60:61], v[174:175], v[60:61] op_sel:[1,0] op_sel_hi:[0,1]
	v_lshlrev_b32_e32 v64, 16, v68
	v_and_b32_e32 v65, 0xffff0000, v68
	v_pk_fma_f32 v[60:61], v[174:175], v[216:217], v[60:61]
	v_mul_f32_e32 v128, v67, v67
	v_pk_fma_f32 v[64:65], v[124:125], v[64:65], v[60:61] op_sel_hi:[0,1,1]
	v_mul_f32_e32 v60, v65, v65
	v_pk_fma_f32 v[60:61], v[64:65], v[64:65], v[60:61] op_sel_hi:[1,1,0]
	v_pk_fma_f32 v[214:215], v[66:67], v[66:67], v[128:129] op_sel_hi:[1,1,0]
	v_pk_add_f32 v[60:61], v[60:61], v[80:81]
	v_mul_f32_e32 v82, v73, v73
	v_pk_add_f32 v[60:61], v[214:215], v[60:61]
	v_pk_fma_f32 v[82:83], v[72:73], v[72:73], v[82:83] op_sel_hi:[1,1,0]
	v_pk_add_f32 v[60:61], v[70:71], v[60:61]
	v_lshlrev_b32_e32 v70, 16, v51
	v_and_b32_e32 v71, 0xffff0000, v55
	v_pk_add_f32 v[68:69], v[82:83], v[60:61]
	v_lshlrev_b32_e32 v60, 16, v55
	v_and_b32_e32 v61, 0xffff0000, v51
	v_pk_mul_f32 v[70:71], v[174:175], v[70:71] op_sel:[1,0] op_sel_hi:[0,1]
	v_pk_fma_f32 v[60:61], v[174:175], v[60:61], v[70:71]
	v_and_b32_e32 v71, 0xffff0000, v50
	v_lshlrev_b32_e32 v50, 16, v50
	v_and_b32_e32 v51, 0xffff0000, v54
	v_lshlrev_b32_e32 v70, 16, v54
	v_pk_mul_f32 v[50:51], v[174:175], v[50:51] op_sel:[1,0] op_sel_hi:[0,1]
	v_lshlrev_b32_e32 v54, 16, v58
	v_and_b32_e32 v55, 0xffff0000, v58
	v_pk_fma_f32 v[50:51], v[174:175], v[70:71], v[50:51]
	v_lshlrev_b32_e32 v70, 16, v49
; __device__ __forceinline__ float bf2f(bf16_t b) { return __uint_as_float(((unsigned)b) << 16); }
; __device__ void phase_mixin(const Params& p, unsigned char* smem, int wave) {
;     ...
;           float ss = 0.f;
; #pragma unroll
;           for (int q = 0; q < 8; ++q) { const u32x4 a = av[q], b = bv[q], c = cv[q];
; #pragma unroll
;               for (int j = 0; j < 4; ++j) { const float lo = w0 * bf2f((bf16_t)a[j]) + w1 * bf2f((bf16_t)b[j]) + w2 * bf2f((bf16_t)c[j]);
;                   const float hi = w0 * bf2f((bf16_t)(a[j] >> 16)) + w1 * bf2f((bf16_t)(b[j] >> 16)) + w2 * bf2f((bf16_t)(c[j] >> 16)); ss += lo * lo + hi * hi; } }
	v_pk_fma_f32 v[50:51], v[124:125], v[54:55], v[50:51] op_sel_hi:[0,1,1]
	v_mul_f32_e32 v54, v51, v51
	v_and_b32_e32 v71, 0xffff0000, v53
	v_lshlrev_b32_e32 v80, 16, v59
	v_and_b32_e32 v81, 0xffff0000, v59
	v_pk_fma_f32 v[58:59], v[50:51], v[50:51], v[54:55] op_sel_hi:[1,1,0]
	v_lshlrev_b32_e32 v54, 16, v53
	v_and_b32_e32 v55, 0xffff0000, v49
	v_pk_mul_f32 v[70:71], v[174:175], v[70:71] op_sel:[1,0] op_sel_hi:[0,1]
	v_pk_fma_f32 v[60:61], v[124:125], v[80:81], v[60:61] op_sel_hi:[0,1,1]
	v_lshlrev_b32_e32 v80, 16, v57
	v_and_b32_e32 v81, 0xffff0000, v57
	v_pk_fma_f32 v[54:55], v[174:175], v[54:55], v[70:71]
	v_and_b32_e32 v49, 0xffff0000, v52
	v_pk_fma_f32 v[54:55], v[124:125], v[80:81], v[54:55] op_sel_hi:[0,1,1]
	v_and_b32_e32 v81, 0xffff0000, v48
	v_lshlrev_b32_e32 v48, 16, v48
	v_lshlrev_b32_e32 v80, 16, v52
	v_pk_mul_f32 v[48:49], v[174:175], v[48:49] op_sel:[1,0] op_sel_hi:[0,1]
	v_lshlrev_b32_e32 v52, 16, v56
	v_and_b32_e32 v53, 0xffff0000, v56
	v_pk_fma_f32 v[48:49], v[174:175], v[80:81], v[48:49]
	v_mul_f32_e32 v70, v55, v55
	v_pk_fma_f32 v[52:53], v[124:125], v[52:53], v[48:49] op_sel_hi:[0,1,1]
	v_mul_f32_e32 v48, v53, v53
	v_pk_fma_f32 v[48:49], v[52:53], v[52:53], v[48:49] op_sel_hi:[1,1,0]
	v_pk_fma_f32 v[70:71], v[54:55], v[54:55], v[70:71] op_sel_hi:[1,1,0]
	v_pk_add_f32 v[48:49], v[48:49], v[68:69]
	v_lshlrev_b32_e32 v68, 16, v47
	v_pk_add_f32 v[48:49], v[70:71], v[48:49]
	v_and_b32_e32 v69, 0xffff0000, v47
	v_pk_add_f32 v[56:57], v[58:59], v[48:49]
	v_lshlrev_b32_e32 v58, 16, v39
	v_and_b32_e32 v59, 0xffff0000, v43
	v_lshlrev_b32_e32 v48, 16, v43
	v_and_b32_e32 v49, 0xffff0000, v39
	v_pk_mul_f32 v[58:59], v[174:175], v[58:59] op_sel:[1,0] op_sel_hi:[0,1]
	v_pk_fma_f32 v[48:49], v[174:175], v[48:49], v[58:59]
	v_and_b32_e32 v59, 0xffff0000, v38
	v_lshlrev_b32_e32 v38, 16, v38
	v_and_b32_e32 v39, 0xffff0000, v42
	v_lshlrev_b32_e32 v58, 16, v42
	v_pk_mul_f32 v[38:39], v[174:175], v[38:39] op_sel:[1,0] op_sel_hi:[0,1]
	v_lshlrev_b32_e32 v42, 16, v46
	v_and_b32_e32 v43, 0xffff0000, v46
	v_pk_fma_f32 v[38:39], v[174:175], v[58:59], v[38:39]
	v_lshlrev_b32_e32 v46, 16, v37
	v_and_b32_e32 v47, 0xffff0000, v41
	v_pk_fma_f32 v[38:39], v[124:125], v[42:43], v[38:39] op_sel_hi:[0,1,1]
	v_lshlrev_b32_e32 v42, 16, v41
	v_and_b32_e32 v43, 0xffff0000, v37
	v_pk_mul_f32 v[46:47], v[174:175], v[46:47] op_sel:[1,0] op_sel_hi:[0,1]
	v_lshlrev_b32_e32 v58, 16, v45
	v_and_b32_e32 v59, 0xffff0000, v45
	v_pk_fma_f32 v[42:43], v[174:175], v[42:43], v[46:47]
	v_mov_b32_e32 v46, v38
	v_pk_fma_f32 v[42:43], v[124:125], v[58:59], v[42:43] op_sel_hi:[0,1,1]
	v_mov_b32_e32 v58, v39
	v_mov_b32_e32 v59, v43
	v_mov_b32_e32 v47, v42
	v_pk_mul_f32 v[58:59], v[58:59], v[58:59]
	v_and_b32_e32 v37, 0xffff0000, v40
	v_pk_fma_f32 v[46:47], v[46:47], v[46:47], v[58:59]
	v_and_b32_e32 v59, 0xffff0000, v36
	v_lshlrev_b32_e32 v36, 16, v36
	v_lshlrev_b32_e32 v58, 16, v40
	v_pk_mul_f32 v[36:37], v[174:175], v[36:37] op_sel:[1,0] op_sel_hi:[0,1]
	v_lshlrev_b32_e32 v40, 16, v44
	v_and_b32_e32 v41, 0xffff0000, v44
	v_pk_fma_f32 v[36:37], v[174:175], v[58:59], v[36:37]
	v_mov_b32_e32 v45, v61
	v_pk_fma_f32 v[40:41], v[124:125], v[40:41], v[36:37] op_sel_hi:[0,1,1]
	v_mov_b32_e32 v44, v41
	v_mov_b32_e32 v36, v40
	v_mov_b32_e32 v37, v60
	v_pk_mul_f32 v[44:45], v[44:45], v[44:45]
	v_pk_fma_f32 v[48:49], v[124:125], v[68:69], v[48:49] op_sel_hi:[0,1,1]
	v_pk_fma_f32 v[36:37], v[36:37], v[36:37], v[44:45]
	v_pk_mul_f32 v[172:173], v[150:151], v[150:151]
	v_pk_add_f32 v[44:45], v[36:37], v[56:57] op_sel:[1,0] op_sel_hi:[0,1]
	v_pk_add_f32 v[36:37], v[36:37], v[44:45]
	v_lshlrev_b32_e32 v56, 16, v35
	v_pk_add_f32 v[36:37], v[46:47], v[36:37] op_sel:[1,0] op_sel_hi:[0,1]
	v_pk_add_f32 v[44:45], v[46:47], v[36:37]
	v_lshlrev_b32_e32 v46, 16, v27
	v_and_b32_e32 v47, 0xffff0000, v31
	v_lshlrev_b32_e32 v36, 16, v31
	v_and_b32_e32 v37, 0xffff0000, v27
	v_pk_mul_f32 v[46:47], v[174:175], v[46:47] op_sel:[1,0] op_sel_hi:[0,1]
	v_pk_fma_f32 v[36:37], v[174:175], v[36:37], v[46:47]
	v_and_b32_e32 v47, 0xffff0000, v26
	v_lshlrev_b32_e32 v26, 16, v26
	v_and_b32_e32 v27, 0xffff0000, v30
	v_lshlrev_b32_e32 v46, 16, v30
	v_pk_mul_f32 v[26:27], v[174:175], v[26:27] op_sel:[1,0] op_sel_hi:[0,1]
	v_and_b32_e32 v57, 0xffff0000, v35
	v_lshlrev_b32_e32 v30, 16, v34
	v_and_b32_e32 v31, 0xffff0000, v34
	v_pk_fma_f32 v[26:27], v[174:175], v[46:47], v[26:27]
	v_lshlrev_b32_e32 v34, 16, v25
	v_and_b32_e32 v35, 0xffff0000, v29
	v_pk_fma_f32 v[26:27], v[124:125], v[30:31], v[26:27] op_sel_hi:[0,1,1]
	v_lshlrev_b32_e32 v30, 16, v29
	v_and_b32_e32 v31, 0xffff0000, v25
	v_pk_mul_f32 v[34:35], v[174:175], v[34:35] op_sel:[1,0] op_sel_hi:[0,1]
	v_lshlrev_b32_e32 v46, 16, v33
	v_and_b32_e32 v47, 0xffff0000, v33
	v_pk_fma_f32 v[30:31], v[174:175], v[30:31], v[34:35]
	v_mov_b32_e32 v34, v26
	v_pk_fma_f32 v[30:31], v[124:125], v[46:47], v[30:31] op_sel_hi:[0,1,1]
	v_mov_b32_e32 v46, v27
	v_mov_b32_e32 v47, v31
	v_mov_b32_e32 v35, v30
	v_pk_mul_f32 v[46:47], v[46:47], v[46:47]
	v_and_b32_e32 v25, 0xffff0000, v28
	v_pk_fma_f32 v[34:35], v[34:35], v[34:35], v[46:47]
	v_and_b32_e32 v47, 0xffff0000, v24
	v_lshlrev_b32_e32 v24, 16, v24
	v_lshlrev_b32_e32 v46, 16, v28
	v_pk_mul_f32 v[24:25], v[174:175], v[24:25] op_sel:[1,0] op_sel_hi:[0,1]
	v_lshlrev_b32_e32 v28, 16, v32
	v_and_b32_e32 v29, 0xffff0000, v32
	v_pk_fma_f32 v[24:25], v[174:175], v[46:47], v[24:25]
	v_mov_b32_e32 v33, v49
	v_pk_fma_f32 v[28:29], v[124:125], v[28:29], v[24:25] op_sel_hi:[0,1,1]
	v_mov_b32_e32 v32, v29
	v_mov_b32_e32 v24, v28
	v_mov_b32_e32 v25, v48
	v_pk_mul_f32 v[32:33], v[32:33], v[32:33]
	v_pk_fma_f32 v[36:37], v[124:125], v[56:57], v[36:37] op_sel_hi:[0,1,1]
; __device__ __forceinline__ float bf2f(bf16_t b) { return __uint_as_float(((unsigned)b) << 16); }
; __device__ void phase_mixin(const Params& p, unsigned char* smem, int wave) {
;     ...
;           float ss = 0.f;
; #pragma unroll
;           for (int q = 0; q < 8; ++q) { const u32x4 a = av[q], b = bv[q], c = cv[q];
; #pragma unroll
;               for (int j = 0; j < 4; ++j) { const float lo = w0 * bf2f((bf16_t)a[j]) + w1 * bf2f((bf16_t)b[j]) + w2 * bf2f((bf16_t)c[j]);
;                   const float hi = w0 * bf2f((bf16_t)(a[j] >> 16)) + w1 * bf2f((bf16_t)(b[j] >> 16)) + w2 * bf2f((bf16_t)(c[j] >> 16)); ss += lo * lo + hi * hi; } }
;           ss += __shfl_xor(ss, 1); ss += __shfl_xor(ss, 2); ss += __shfl_xor(ss, 4);
	v_pk_fma_f32 v[24:25], v[24:25], v[24:25], v[32:33]
	v_lshlrev_b32_e32 v221, 16, v93
	v_pk_add_f32 v[32:33], v[24:25], v[44:45] op_sel:[1,0] op_sel_hi:[0,1]
	v_pk_add_f32 v[24:25], v[24:25], v[32:33]
	v_lshlrev_b32_e32 v44, 16, v23
	v_pk_add_f32 v[24:25], v[34:35], v[24:25] op_sel:[1,0] op_sel_hi:[0,1]
	v_pk_add_f32 v[32:33], v[34:35], v[24:25]
	v_lshlrev_b32_e32 v34, 16, v15
	v_and_b32_e32 v35, 0xffff0000, v19
	v_lshlrev_b32_e32 v24, 16, v19
	v_and_b32_e32 v25, 0xffff0000, v15
	v_pk_mul_f32 v[34:35], v[174:175], v[34:35] op_sel:[1,0] op_sel_hi:[0,1]
	v_pk_fma_f32 v[24:25], v[174:175], v[24:25], v[34:35]
	v_and_b32_e32 v35, 0xffff0000, v14
	v_lshlrev_b32_e32 v14, 16, v14
	v_and_b32_e32 v15, 0xffff0000, v18
	v_lshlrev_b32_e32 v34, 16, v18
	v_pk_mul_f32 v[14:15], v[174:175], v[14:15] op_sel:[1,0] op_sel_hi:[0,1]
	v_and_b32_e32 v45, 0xffff0000, v23
	v_lshlrev_b32_e32 v18, 16, v22
	v_and_b32_e32 v19, 0xffff0000, v22
	v_pk_fma_f32 v[14:15], v[174:175], v[34:35], v[14:15]
	v_lshlrev_b32_e32 v22, 16, v13
	v_and_b32_e32 v23, 0xffff0000, v17
	v_pk_fma_f32 v[14:15], v[124:125], v[18:19], v[14:15] op_sel_hi:[0,1,1]
	v_lshlrev_b32_e32 v18, 16, v17
	v_and_b32_e32 v19, 0xffff0000, v13
	v_pk_mul_f32 v[22:23], v[174:175], v[22:23] op_sel:[1,0] op_sel_hi:[0,1]
	v_lshlrev_b32_e32 v34, 16, v21
	v_and_b32_e32 v35, 0xffff0000, v21
	v_pk_fma_f32 v[18:19], v[174:175], v[18:19], v[22:23]
	v_mov_b32_e32 v22, v14
	v_pk_fma_f32 v[18:19], v[124:125], v[34:35], v[18:19] op_sel_hi:[0,1,1]
	v_mov_b32_e32 v34, v15
	v_mov_b32_e32 v35, v19
	v_mov_b32_e32 v23, v18
	v_pk_mul_f32 v[34:35], v[34:35], v[34:35]
	v_and_b32_e32 v13, 0xffff0000, v16
	v_pk_fma_f32 v[22:23], v[22:23], v[22:23], v[34:35]
	v_and_b32_e32 v35, 0xffff0000, v12
	v_lshlrev_b32_e32 v12, 16, v12
	v_lshlrev_b32_e32 v34, 16, v16
	v_pk_mul_f32 v[12:13], v[174:175], v[12:13] op_sel:[1,0] op_sel_hi:[0,1]
	v_lshlrev_b32_e32 v16, 16, v20
	v_and_b32_e32 v17, 0xffff0000, v20
	v_pk_fma_f32 v[12:13], v[174:175], v[34:35], v[12:13]
	v_mov_b32_e32 v21, v37
	v_pk_fma_f32 v[16:17], v[124:125], v[16:17], v[12:13] op_sel_hi:[0,1,1]
	v_mov_b32_e32 v20, v17
	v_mov_b32_e32 v12, v16
	v_mov_b32_e32 v13, v36
	v_pk_mul_f32 v[20:21], v[20:21], v[20:21]
	v_pk_fma_f32 v[24:25], v[124:125], v[44:45], v[24:25] op_sel_hi:[0,1,1]
	v_pk_fma_f32 v[12:13], v[12:13], v[12:13], v[20:21]
	v_mov_b32_e32 v154, v24
	v_pk_add_f32 v[20:21], v[12:13], v[32:33] op_sel:[1,0] op_sel_hi:[0,1]
	v_pk_add_f32 v[12:13], v[12:13], v[20:21]
	v_lshlrev_b32_e32 v32, 16, v11
	v_pk_add_f32 v[12:13], v[22:23], v[12:13] op_sel:[1,0] op_sel_hi:[0,1]
	v_pk_add_f32 v[20:21], v[22:23], v[12:13]
	v_lshlrev_b32_e32 v22, 16, v3
	v_and_b32_e32 v23, 0xffff0000, v7
	v_lshlrev_b32_e32 v12, 16, v7
	v_and_b32_e32 v13, 0xffff0000, v3
	v_pk_mul_f32 v[22:23], v[174:175], v[22:23] op_sel:[1,0] op_sel_hi:[0,1]
	v_pk_fma_f32 v[12:13], v[174:175], v[12:13], v[22:23]
	v_and_b32_e32 v23, 0xffff0000, v2
	v_lshlrev_b32_e32 v2, 16, v2
	v_and_b32_e32 v3, 0xffff0000, v6
	v_lshlrev_b32_e32 v22, 16, v6
	v_pk_mul_f32 v[2:3], v[174:175], v[2:3] op_sel:[1,0] op_sel_hi:[0,1]
	v_and_b32_e32 v33, 0xffff0000, v11
	v_lshlrev_b32_e32 v6, 16, v10
	v_and_b32_e32 v7, 0xffff0000, v10
	v_pk_fma_f32 v[2:3], v[174:175], v[22:23], v[2:3]
	v_pk_fma_f32 v[12:13], v[124:125], v[32:33], v[12:13] op_sel_hi:[0,1,1]
	v_pk_fma_f32 v[2:3], v[124:125], v[6:7], v[2:3] op_sel_hi:[0,1,1]
	v_mov_b32_e32 v10, v13
	v_mov_b32_e32 v11, v3
	v_mov_b32_e32 v6, v12
	v_mov_b32_e32 v7, v2
	v_pk_mul_f32 v[10:11], v[10:11], v[10:11]
	v_lshlrev_b32_e32 v22, 16, v1
	v_and_b32_e32 v23, 0xffff0000, v5
	v_pk_fma_f32 v[10:11], v[6:7], v[6:7], v[10:11]
	v_lshlrev_b32_e32 v6, 16, v5
	v_and_b32_e32 v7, 0xffff0000, v1
	v_pk_mul_f32 v[22:23], v[174:175], v[22:23] op_sel:[1,0] op_sel_hi:[0,1]
	v_pk_fma_f32 v[6:7], v[174:175], v[6:7], v[22:23]
	v_and_b32_e32 v23, 0xffff0000, v0
	v_lshlrev_b32_e32 v0, 16, v0
	v_and_b32_e32 v1, 0xffff0000, v4
	v_lshlrev_b32_e32 v22, 16, v4
	v_pk_mul_f32 v[0:1], v[174:175], v[0:1] op_sel:[1,0] op_sel_hi:[0,1]
	v_lshlrev_b32_e32 v32, 16, v9
	v_and_b32_e32 v33, 0xffff0000, v9
	v_lshlrev_b32_e32 v4, 16, v8
	v_and_b32_e32 v5, 0xffff0000, v8
	v_pk_fma_f32 v[0:1], v[174:175], v[22:23], v[0:1]
	v_pk_fma_f32 v[6:7], v[124:125], v[32:33], v[6:7] op_sel_hi:[0,1,1]
	v_pk_fma_f32 v[4:5], v[124:125], v[4:5], v[0:1] op_sel_hi:[0,1,1]
	v_mov_b32_e32 v8, v7
	v_mov_b32_e32 v9, v5
	v_mov_b32_e32 v0, v6
	v_mov_b32_e32 v1, v4
	v_pk_mul_f32 v[8:9], v[8:9], v[8:9]
	v_mul_f32_e32 v170, v25, v25
	v_pk_fma_f32 v[0:1], v[0:1], v[0:1], v[8:9]
	v_pk_fma_f32 v[8:9], v[154:155], v[154:155], v[170:171]
	v_mov_b32_e32 v21, v212
	v_lshlrev_b32_e32 v220, 16, v92
	v_and_b32_e32 v93, 0xffff0000, v93
	v_and_b32_e32 v92, 0xffff0000, v92
	v_pk_add_f32 v[8:9], v[8:9], v[20:21]
	v_pk_mov_b32 v[20:21], v[0:1], v[172:173] op_sel:[1,0]
	v_pk_fma_f32 v[84:85], v[124:125], v[92:93], v[84:85] op_sel_hi:[0,1,1]
	v_pk_add_f32 v[8:9], v[20:21], v[8:9]
	v_mov_b32_e32 v1, v173
	v_pk_fma_f32 v[88:89], v[124:125], v[220:221], v[88:89] op_sel_hi:[0,1,1]
	v_pk_mul_f32 v[92:93], v[84:85], v[84:85]
	v_lshlrev_b32_e32 v221, 16, v95
	v_lshlrev_b32_e32 v220, 16, v94
	v_and_b32_e32 v95, 0xffff0000, v95
	v_and_b32_e32 v94, 0xffff0000, v94
	v_pk_add_f32 v[0:1], v[0:1], v[8:9]
	v_pk_mov_b32 v[8:9], v[10:11], v[168:169] op_sel:[1,0]
	v_pk_fma_f32 v[92:93], v[88:89], v[88:89], v[92:93]
	v_pk_fma_f32 v[86:87], v[124:125], v[94:95], v[86:87] op_sel_hi:[0,1,1]
	v_pk_add_f32 v[0:1], v[8:9], v[0:1]
	v_mov_b32_e32 v11, v169
	v_pk_fma_f32 v[90:91], v[124:125], v[220:221], v[90:91] op_sel_hi:[0,1,1]
	v_pk_mul_f32 v[94:95], v[86:87], v[86:87]
	v_pk_add_f32 v[0:1], v[10:11], v[0:1]
	v_mov_b32_e32 v8, v92
	v_mov_b32_e32 v9, v164
	v_pk_fma_f32 v[94:95], v[90:91], v[90:91], v[94:95]
	v_pk_add_f32 v[0:1], v[8:9], v[0:1]
	v_mov_b32_e32 v164, v93
	v_pk_add_f32 v[0:1], v[164:165], v[0:1]
	v_mov_b32_e32 v8, v94
	v_mov_b32_e32 v9, v162
	v_pk_add_f32 v[0:1], v[8:9], v[0:1]
	v_mov_b32_e32 v162, v95
	v_pk_add_f32 v[0:1], v[162:163], v[0:1]
	ds_bpermute_b32 v9, v176, v1
	ds_bpermute_b32 v8, v176, v0
	v_lshlrev_b32_e32 v142, 16, v138
	v_lshlrev_b32_e32 v145, 16, v184
	v_lshlrev_b32_e32 v147, 16, v200
	v_lshlrev_b32_e32 v153, 16, v197
	s_waitcnt lgkmcnt(0)
; __device__ __forceinline__ unsigned pk2(float lo, float hi) { return cvtpk(lo, hi); }
; __device__ __forceinline__ float bf2f(bf16_t b) { return __uint_as_float(((unsigned)b) << 16); }
; __device__ void phase_mixin(const Params& p, unsigned char* smem, int wave) {
;     ...
;           const float r = rsqrtf(ss * (1.f / 512.f) + EPS);
;           bf16_t* dst = mix + (size_t)g * D + sub * 64;
; #pragma unroll
;           for (int q = 0; q < 8; ++q) { float v[8];
; #pragma unroll
;               for (int j = 0; j < 8; ++j) { const int c = sub * 64 + 8 * q + j; v[j] = bf2f(tl[c * 66 + tt]) * r * p.hy_out_g[c]; }
;               u32x4 w; w.x = pk2(v[0], v[1]); w.y = pk2(v[2], v[3]); w.z = pk2(v[4], v[5]); w.w = pk2(v[6], v[7]);
;               *(u32x4*)(dst + 8 * q) = w; } }
	v_pk_add_f32 v[0:1], v[0:1], v[8:9]
	ds_bpermute_b32 v9, v177, v1
	ds_bpermute_b32 v8, v177, v0
	v_lshlrev_b32_e32 v151, 16, v202
	s_waitcnt lgkmcnt(0)
	v_pk_add_f32 v[0:1], v[0:1], v[8:9]
	ds_bpermute_b32 v9, v178, v1
	ds_bpermute_b32 v8, v178, v0
	s_waitcnt lgkmcnt(0)
	v_pk_add_f32 v[0:1], v[0:1], v[8:9]
	s_nop 0
	v_pk_fma_f32 v[32:33], v[0:1], s[8:9], v[120:121] op_sel_hi:[1,0,0]
	s_nop 0
	v_mul_f32_e32 v0, 0x4b800000, v33
	v_cmp_gt_f32_e32 vcc, s12, v33
	s_nop 1
	v_cndmask_b32_e32 v0, v33, v0, vcc
	v_rsq_f32_e32 v8, v0
	v_lshlrev_b64 v[0:1], 11, v[122:123]
	v_lshl_add_u64 v[0:1], v[118:119], 0, v[0:1]
	v_mul_f32_e32 v9, 0x45800000, v8
	v_cndmask_b32_e32 v34, v8, v9, vcc
	v_pk_mul_f32 v[8:9], v[34:35], v[166:167] op_sel_hi:[0,1]
	v_pk_mul_f32 v[10:11], v[34:35], v[160:161] op_sel_hi:[0,1]
	v_pk_mul_f32 v[20:21], v[34:35], v[158:159] op_sel_hi:[0,1]
	v_pk_mul_f32 v[22:23], v[34:35], v[156:157] op_sel_hi:[0,1]
	s_waitcnt lgkmcnt(0)
	v_pk_mul_f32 v[8:9], v[100:101], v[8:9]
	v_pk_mul_f32 v[10:11], v[102:103], v[10:11]
	v_pk_mul_f32 v[20:21], v[96:97], v[20:21]
	v_pk_mul_f32 v[22:23], v[98:99], v[22:23]
	v_cvt_pk_bf16_f32 v8, v8, v9
	v_cvt_pk_bf16_f32 v9, v10, v11
	v_cvt_pk_bf16_f32 v10, v20, v21
	v_cvt_pk_bf16_f32 v11, v22, v23
	global_store_dwordx4 v[0:1], v[8:11], off
	s_nop 1
	ds_read_b128 v[8:11], v230 offset:32
	s_nop 0
	ds_read_b128 v[20:23], v230 offset:48
	ds_read_u16 v33, v183
	v_cmp_gt_f32_e32 vcc, s12, v32
	s_waitcnt lgkmcnt(0)
	v_lshlrev_b32_e32 v132, 16, v33
	ds_read_u16 v33, v183 offset:528
	ds_read_u16 v35, v183 offset:1056
	ds_read_u16 v46, v183 offset:1320
	ds_read_u16 v47, v183 offset:1584
	ds_read_u16 v56, v183 offset:2112
	ds_read_u16 v57, v183 offset:2376
	ds_read_u16 v58, v183 offset:2640
	s_waitcnt lgkmcnt(5)
	v_pk_mul_f32 v[44:45], v[34:35], v[134:135] op_sel_hi:[0,1]
	v_lshlrev_b32_e32 v140, 16, v33
	v_lshlrev_b32_e32 v128, 16, v35
	s_waitcnt lgkmcnt(4)
	v_lshlrev_b32_e32 v138, 16, v46
	s_waitcnt lgkmcnt(3)
	v_lshlrev_b32_e32 v136, 16, v47
	s_waitcnt lgkmcnt(2)
	v_lshlrev_b32_e32 v124, 16, v56
	s_waitcnt lgkmcnt(0)
	v_pk_mul_f32 v[8:9], v[8:9], v[44:45]
	v_pk_mul_f32 v[44:45], v[34:35], v[132:133] op_sel_hi:[0,1]
	v_pk_mul_f32 v[10:11], v[10:11], v[44:45]
	v_pk_mul_f32 v[44:45], v[34:35], v[142:143] op_sel_hi:[0,1]
	s_waitcnt lgkmcnt(0)
	v_pk_mul_f32 v[20:21], v[20:21], v[44:45]
	v_pk_mul_f32 v[44:45], v[34:35], v[140:141] op_sel_hi:[0,1]
	v_pk_mul_f32 v[22:23], v[22:23], v[44:45]
	v_cvt_pk_bf16_f32 v8, v8, v9
	v_cvt_pk_bf16_f32 v9, v10, v11
	v_cvt_pk_bf16_f32 v10, v20, v21
	v_cvt_pk_bf16_f32 v11, v22, v23
	global_store_dwordx4 v[0:1], v[8:11], off offset:16
	s_nop 1
	ds_read_b128 v[8:11], v230 offset:64
	s_nop 0
	ds_read_b128 v[20:23], v230 offset:80
	v_pk_mul_f32 v[44:45], v[34:35], v[130:131] op_sel_hi:[0,1]
	s_waitcnt lgkmcnt(0)
	v_pk_mul_f32 v[8:9], v[44:45], v[8:9]
	v_pk_mul_f32 v[44:45], v[34:35], v[128:129] op_sel_hi:[0,1]
	v_pk_mul_f32 v[10:11], v[10:11], v[44:45]
	v_pk_mul_f32 v[44:45], v[34:35], v[138:139] op_sel_hi:[0,1]
	s_waitcnt lgkmcnt(0)
	v_pk_mul_f32 v[20:21], v[20:21], v[44:45]
	v_pk_mul_f32 v[44:45], v[34:35], v[136:137] op_sel_hi:[0,1]
	v_pk_mul_f32 v[22:23], v[22:23], v[44:45]
	v_cvt_pk_bf16_f32 v8, v8, v9
	v_cvt_pk_bf16_f32 v9, v10, v11
	v_cvt_pk_bf16_f32 v10, v20, v21
	v_cvt_pk_bf16_f32 v11, v22, v23
	global_store_dwordx4 v[0:1], v[8:11], off offset:32
	s_nop 1
	ds_read_b128 v[8:11], v230 offset:96
	s_nop 0
	ds_read_b128 v[20:23], v230 offset:112
	v_pk_mul_f32 v[44:45], v[34:35], v[126:127] op_sel_hi:[0,1]
	s_waitcnt lgkmcnt(0)
	v_pk_mul_f32 v[8:9], v[44:45], v[8:9]
	v_pk_mul_f32 v[44:45], v[34:35], v[124:125] op_sel_hi:[0,1]
	v_pk_mul_f32 v[10:11], v[10:11], v[44:45]
	v_lshlrev_b32_e32 v45, 16, v187
	s_waitcnt lgkmcnt(1)
	v_lshlrev_b32_e32 v44, 16, v57
	v_pk_mul_f32 v[44:45], v[34:35], v[44:45] op_sel_hi:[0,1]
	s_waitcnt lgkmcnt(0)
	v_pk_mul_f32 v[20:21], v[20:21], v[44:45]
	v_lshlrev_b32_e32 v45, 16, v186
	s_waitcnt lgkmcnt(0)
	v_lshlrev_b32_e32 v44, 16, v58
	v_pk_mul_f32 v[44:45], v[34:35], v[44:45] op_sel_hi:[0,1]
	v_pk_mul_f32 v[22:23], v[22:23], v[44:45]
	v_cvt_pk_bf16_f32 v8, v8, v9
	v_cvt_pk_bf16_f32 v9, v10, v11
	v_cvt_pk_bf16_f32 v10, v20, v21
	v_cvt_pk_bf16_f32 v11, v22, v23
	global_store_dwordx4 v[0:1], v[8:11], off offset:48
	s_nop 1
	ds_read_b128 v[8:11], v230 offset:128
	s_nop 0
	ds_read_b128 v[20:23], v230 offset:144
	ds_read_u16 v33, v182 offset:528
	v_pk_mul_f32 v[44:45], v[34:35], v[144:145] op_sel_hi:[0,1]
	s_waitcnt lgkmcnt(0)
	v_pk_mul_f32 v[8:9], v[44:45], v[8:9]
	v_lshlrev_b32_e32 v45, 16, v190
	v_lshlrev_b32_e32 v44, 16, v185
	v_pk_mul_f32 v[44:45], v[34:35], v[44:45] op_sel_hi:[0,1]
	v_pk_mul_f32 v[10:11], v[10:11], v[44:45]
	v_lshlrev_b32_e32 v45, 16, v189
	s_waitcnt lgkmcnt(0)
	v_lshlrev_b32_e32 v44, 16, v33
	v_pk_mul_f32 v[44:45], v[34:35], v[44:45] op_sel_hi:[0,1]
	s_waitcnt lgkmcnt(0)
	v_pk_mul_f32 v[20:21], v[20:21], v[44:45]
	v_lshlrev_b32_e32 v45, 16, v188
	v_lshlrev_b32_e32 v44, 16, v199
	v_pk_mul_f32 v[44:45], v[34:35], v[44:45] op_sel_hi:[0,1]
	v_pk_mul_f32 v[22:23], v[22:23], v[44:45]
	v_cvt_pk_bf16_f32 v8, v8, v9
	v_cvt_pk_bf16_f32 v9, v10, v11
	v_cvt_pk_bf16_f32 v10, v20, v21
	v_cvt_pk_bf16_f32 v11, v22, v23
	global_store_dwordx4 v[0:1], v[8:11], off offset:64
	s_nop 1
	ds_read_b128 v[8:11], v230 offset:160
	s_nop 0
	ds_read_b128 v[20:23], v230 offset:176
	v_pk_mul_f32 v[44:45], v[34:35], v[146:147] op_sel_hi:[0,1]
	s_waitcnt lgkmcnt(0)
	v_pk_mul_f32 v[8:9], v[44:45], v[8:9]
	v_lshlrev_b32_e32 v45, 16, v198
	v_lshlrev_b32_e32 v44, 16, v191
	v_pk_mul_f32 v[44:45], v[34:35], v[44:45] op_sel_hi:[0,1]
	v_pk_mul_f32 v[10:11], v[10:11], v[44:45]
	v_lshlrev_b32_e32 v45, 16, v196
	v_lshlrev_b32_e32 v44, 16, v192
	v_pk_mul_f32 v[44:45], v[34:35], v[44:45] op_sel_hi:[0,1]
	s_waitcnt lgkmcnt(0)
; __device__ __forceinline__ unsigned pk2(float lo, float hi) { return cvtpk(lo, hi); }
; __device__ __forceinline__ float bf2f(bf16_t b) { return __uint_as_float(((unsigned)b) << 16); }
; __device__ void phase_mixin(const Params& p, unsigned char* smem, int wave) {
;     ...
;           const float r = rsqrtf(ss * (1.f / 512.f) + EPS);
;           bf16_t* dst = mix + (size_t)g * D + sub * 64;
; #pragma unroll
;           for (int q = 0; q < 8; ++q) { float v[8];
; #pragma unroll
;               for (int j = 0; j < 8; ++j) { const int c = sub * 64 + 8 * q + j; v[j] = bf2f(tl[c * 66 + tt]) * r * p.hy_out_g[c]; }
;               u32x4 w; w.x = pk2(v[0], v[1]); w.y = pk2(v[2], v[3]); w.z = pk2(v[4], v[5]); w.w = pk2(v[6], v[7]);
;               *(u32x4*)(dst + 8 * q) = w; } }
;     ...
;           const float r = rsqrtf(ss * (1.f / 512.f) + EPS);
;           bf16_t* dst = mix + (size_t)g * D + 512 + h * 64; const float* ag = p.attn_out_g + h * 64;
; #pragma unroll
;           for (int q = 0; q < 8; ++q) { const u32x4 a = av[q], b = bv[q], c = cv[q]; u32x4 w;
; #pragma unroll
;               for (int j = 0; j < 4; ++j) { const float lo = w0 * bf2f((bf16_t)a[j]) + w1 * bf2f((bf16_t)b[j]) + w2 * bf2f((bf16_t)c[j]);
;                   const float hi = w0 * bf2f((bf16_t)(a[j] >> 16)) + w1 * bf2f((bf16_t)(b[j] >> 16)) + w2 * bf2f((bf16_t)(c[j] >> 16));
;                   w[j] = pk2(lo * r * ag[8 * q + 2 * j], hi * r * ag[8 * q + 2 * j + 1]); }
;               *(u32x4*)(dst + 8 * q) = w; } }
	v_pk_mul_f32 v[20:21], v[20:21], v[44:45]
	v_lshlrev_b32_e32 v45, 16, v201
	v_lshlrev_b32_e32 v44, 16, v194
	v_pk_mul_f32 v[44:45], v[34:35], v[44:45] op_sel_hi:[0,1]
	v_pk_mul_f32 v[22:23], v[22:23], v[44:45]
	v_cvt_pk_bf16_f32 v8, v8, v9
	v_cvt_pk_bf16_f32 v9, v10, v11
	v_cvt_pk_bf16_f32 v10, v20, v21
	v_cvt_pk_bf16_f32 v11, v22, v23
	global_store_dwordx4 v[0:1], v[8:11], off offset:80
	s_nop 1
	ds_read_b128 v[8:11], v230 offset:192
	s_nop 0
	ds_read_b128 v[20:23], v230 offset:208
	ds_read_u16 v33, v182 offset:2640
	v_pk_mul_f32 v[44:45], v[34:35], v[152:153] op_sel_hi:[0,1]
	s_waitcnt lgkmcnt(0)
	v_pk_mul_f32 v[8:9], v[44:45], v[8:9]
	v_lshlrev_b32_e32 v45, 16, v195
	v_lshlrev_b32_e32 v44, 16, v193
	v_pk_mul_f32 v[44:45], v[34:35], v[44:45] op_sel_hi:[0,1]
	v_pk_mul_f32 v[10:11], v[10:11], v[44:45]
	v_lshlrev_b32_e32 v45, 16, v204
	s_waitcnt lgkmcnt(0)
	v_lshlrev_b32_e32 v44, 16, v33
	v_pk_mul_f32 v[44:45], v[34:35], v[44:45] op_sel_hi:[0,1]
	s_waitcnt lgkmcnt(0)
	v_pk_mul_f32 v[20:21], v[20:21], v[44:45]
	v_lshlrev_b32_e32 v45, 16, v203
	v_lshlrev_b32_e32 v44, 16, v211
	v_pk_mul_f32 v[44:45], v[34:35], v[44:45] op_sel_hi:[0,1]
	v_pk_mul_f32 v[22:23], v[22:23], v[44:45]
	v_cvt_pk_bf16_f32 v8, v8, v9
	v_cvt_pk_bf16_f32 v9, v10, v11
	v_cvt_pk_bf16_f32 v10, v20, v21
	v_cvt_pk_bf16_f32 v11, v22, v23
	global_store_dwordx4 v[0:1], v[8:11], off offset:96
	s_nop 1
	ds_read_b128 v[8:11], v230 offset:224
	s_nop 0
	ds_read_b128 v[20:23], v230 offset:240
	v_pk_mul_f32 v[44:45], v[34:35], v[150:151] op_sel_hi:[0,1]
	v_mul_f32_e32 v33, 0x4b800000, v32
	v_cndmask_b32_e32 v32, v32, v33, vcc
	v_rsq_f32_e32 v32, v32
	s_waitcnt lgkmcnt(0)
	v_pk_mul_f32 v[8:9], v[44:45], v[8:9]
	v_lshlrev_b32_e32 v45, 16, v207
	v_lshlrev_b32_e32 v44, 16, v210
	v_pk_mul_f32 v[44:45], v[34:35], v[44:45] op_sel_hi:[0,1]
	v_pk_mul_f32 v[10:11], v[10:11], v[44:45]
	v_lshlrev_b32_e32 v45, 16, v206
	v_lshlrev_b32_e32 v44, 16, v209
	v_pk_mul_f32 v[44:45], v[34:35], v[44:45] op_sel_hi:[0,1]
	s_waitcnt lgkmcnt(0)
	v_pk_mul_f32 v[20:21], v[20:21], v[44:45]
	v_lshlrev_b32_e32 v45, 16, v205
	v_lshlrev_b32_e32 v44, 16, v208
	v_pk_mul_f32 v[34:35], v[34:35], v[44:45] op_sel_hi:[0,1]
	v_pk_mul_f32 v[22:23], v[22:23], v[34:35]
	v_cvt_pk_bf16_f32 v8, v8, v9
	v_cvt_pk_bf16_f32 v9, v10, v11
	v_cvt_pk_bf16_f32 v10, v20, v21
	v_cvt_pk_bf16_f32 v11, v22, v23
	global_store_dwordx4 v[0:1], v[8:11], off offset:112
	s_nop 1
	ds_read_b128 v[8:11], v230 offset:2176
	s_nop 0
	ds_read_b128 v[20:23], v230 offset:2192
	v_mul_f32_e32 v33, 0x45800000, v32
	v_cndmask_b32_e32 v32, v32, v33, vcc
	v_pk_mul_f32 v[34:35], v[76:77], v[32:33] op_sel_hi:[1,0]
	v_pk_mul_f32 v[44:45], v[54:55], v[32:33] op_sel_hi:[1,0]
	v_pk_mul_f32 v[46:47], v[50:51], v[32:33] op_sel_hi:[1,0]
	v_pk_mul_f32 v[50:51], v[60:61], v[32:33] op_sel_hi:[1,0]
	v_pk_mul_f32 v[38:39], v[38:39], v[32:33] op_sel_hi:[1,0]
	v_pk_mul_f32 v[28:29], v[28:29], v[32:33] op_sel_hi:[1,0]
	v_pk_mul_f32 v[30:31], v[30:31], v[32:33] op_sel_hi:[1,0]
	v_pk_mul_f32 v[26:27], v[26:27], v[32:33] op_sel_hi:[1,0]
	v_pk_mul_f32 v[16:17], v[16:17], v[32:33] op_sel_hi:[1,0]
	v_pk_mul_f32 v[18:19], v[18:19], v[32:33] op_sel_hi:[1,0]
	v_pk_mul_f32 v[14:15], v[14:15], v[32:33] op_sel_hi:[1,0]
	v_pk_mul_f32 v[24:25], v[24:25], v[32:33] op_sel_hi:[1,0]
	v_pk_mul_f32 v[4:5], v[4:5], v[32:33] op_sel_hi:[1,0]
	v_pk_mul_f32 v[6:7], v[6:7], v[32:33] op_sel_hi:[1,0]
	v_pk_mul_f32 v[2:3], v[2:3], v[32:33] op_sel_hi:[1,0]
	v_pk_mul_f32 v[12:13], v[12:13], v[32:33] op_sel_hi:[1,0]
	s_waitcnt lgkmcnt(0)
	v_pk_mul_f32 v[8:9], v[8:9], v[34:35]
	v_pk_mul_f32 v[34:35], v[78:79], v[32:33] op_sel_hi:[1,0]
	v_cvt_pk_bf16_f32 v8, v8, v9
	v_pk_mul_f32 v[10:11], v[10:11], v[34:35]
	v_pk_mul_f32 v[34:35], v[64:65], v[32:33] op_sel_hi:[1,0]
	v_cvt_pk_bf16_f32 v9, v10, v11
	v_pk_mul_f32 v[10:11], v[74:75], v[32:33] op_sel_hi:[1,0]
	s_waitcnt lgkmcnt(0)
	v_pk_mul_f32 v[10:11], v[20:21], v[10:11]
	v_pk_mul_f32 v[20:21], v[148:149], v[32:33] op_sel_hi:[1,0]
	v_cvt_pk_bf16_f32 v10, v10, v11
	v_pk_mul_f32 v[20:21], v[22:23], v[20:21]
	s_nop 0
	v_cvt_pk_bf16_f32 v11, v20, v21
	global_store_dwordx4 v[0:1], v[8:11], off offset:1024
	s_nop 1
	ds_read_b128 v[8:11], v230 offset:2208
	s_nop 0
	ds_read_b128 v[20:23], v230 offset:2224
	s_waitcnt lgkmcnt(0)
; __device__ __forceinline__ unsigned pk2(float lo, float hi) { return cvtpk(lo, hi); }
; __device__ __forceinline__ float bf2f(bf16_t b) { return __uint_as_float(((unsigned)b) << 16); }
; __device__ void phase_mixin(const Params& p, unsigned char* smem, int wave) {
;     ...
;           const float r = rsqrtf(ss * (1.f / 512.f) + EPS);
;           bf16_t* dst = mix + (size_t)g * D + 512 + h * 64; const float* ag = p.attn_out_g + h * 64;
; #pragma unroll
;           for (int q = 0; q < 8; ++q) { const u32x4 a = av[q], b = bv[q], c = cv[q]; u32x4 w;
; #pragma unroll
;               for (int j = 0; j < 4; ++j) { const float lo = w0 * bf2f((bf16_t)a[j]) + w1 * bf2f((bf16_t)b[j]) + w2 * bf2f((bf16_t)c[j]);
;                   const float hi = w0 * bf2f((bf16_t)(a[j] >> 16)) + w1 * bf2f((bf16_t)(b[j] >> 16)) + w2 * bf2f((bf16_t)(c[j] >> 16));
;                   w[j] = pk2(lo * r * ag[8 * q + 2 * j], hi * r * ag[8 * q + 2 * j + 1]); }
;               *(u32x4*)(dst + 8 * q) = w; } }
	v_pk_mul_f32 v[8:9], v[34:35], v[8:9]
	v_pk_mul_f32 v[34:35], v[66:67], v[32:33] op_sel_hi:[1,0]
	v_cvt_pk_bf16_f32 v8, v8, v9
	v_pk_mul_f32 v[10:11], v[34:35], v[10:11]
	v_pk_mul_f32 v[34:35], v[52:53], v[32:33] op_sel_hi:[1,0]
	v_cvt_pk_bf16_f32 v9, v10, v11
	v_pk_mul_f32 v[10:11], v[62:63], v[32:33] op_sel_hi:[1,0]
	s_waitcnt lgkmcnt(0)
	v_pk_mul_f32 v[10:11], v[10:11], v[20:21]
	v_pk_mul_f32 v[20:21], v[72:73], v[32:33] op_sel_hi:[1,0]
	v_cvt_pk_bf16_f32 v10, v10, v11
	v_pk_mul_f32 v[20:21], v[20:21], v[22:23]
	s_nop 0
	v_cvt_pk_bf16_f32 v11, v20, v21
	global_store_dwordx4 v[0:1], v[8:11], off offset:1040
	s_nop 1
	ds_read_b128 v[8:11], v230 offset:2240
	s_nop 0
	ds_read_b128 v[20:23], v230 offset:2256
	s_waitcnt lgkmcnt(0)
	v_pk_mul_f32 v[8:9], v[34:35], v[8:9]
	v_pk_mul_f32 v[10:11], v[44:45], v[10:11]
	s_waitcnt lgkmcnt(0)
	v_pk_mul_f32 v[20:21], v[46:47], v[20:21]
	v_pk_mul_f32 v[22:23], v[50:51], v[22:23]
	v_cvt_pk_bf16_f32 v8, v8, v9
	v_cvt_pk_bf16_f32 v9, v10, v11
	v_cvt_pk_bf16_f32 v10, v20, v21
	v_cvt_pk_bf16_f32 v11, v22, v23
	global_store_dwordx4 v[0:1], v[8:11], off offset:1056
	s_nop 1
	ds_read_b128 v[8:11], v230 offset:2272
	s_nop 0
	ds_read_b128 v[20:23], v230 offset:2288
	v_pk_mul_f32 v[34:35], v[40:41], v[32:33] op_sel_hi:[1,0]
	v_pk_mul_f32 v[40:41], v[42:43], v[32:33] op_sel_hi:[1,0]
	v_pk_mul_f32 v[42:43], v[48:49], v[32:33] op_sel_hi:[1,0]
	s_waitcnt lgkmcnt(0)
	v_pk_mul_f32 v[8:9], v[34:35], v[8:9]
	v_pk_mul_f32 v[10:11], v[40:41], v[10:11]
	s_waitcnt lgkmcnt(0)
	v_pk_mul_f32 v[20:21], v[38:39], v[20:21]
	v_pk_mul_f32 v[22:23], v[42:43], v[22:23]
	v_cvt_pk_bf16_f32 v8, v8, v9
	v_cvt_pk_bf16_f32 v9, v10, v11
	v_cvt_pk_bf16_f32 v10, v20, v21
	v_cvt_pk_bf16_f32 v11, v22, v23
	global_store_dwordx4 v[0:1], v[8:11], off offset:1072
	s_nop 1
	ds_read_b128 v[8:11], v230 offset:2304
	s_nop 0
	ds_read_b128 v[20:23], v230 offset:2320
	v_pk_mul_f32 v[34:35], v[36:37], v[32:33] op_sel_hi:[1,0]
	s_waitcnt lgkmcnt(0)
	v_pk_mul_f32 v[8:9], v[28:29], v[8:9]
	v_pk_mul_f32 v[10:11], v[30:31], v[10:11]
	s_waitcnt lgkmcnt(0)
	v_pk_mul_f32 v[20:21], v[26:27], v[20:21]
	v_pk_mul_f32 v[22:23], v[34:35], v[22:23]
	v_cvt_pk_bf16_f32 v8, v8, v9
	v_cvt_pk_bf16_f32 v9, v10, v11
	v_cvt_pk_bf16_f32 v10, v20, v21
	v_cvt_pk_bf16_f32 v11, v22, v23
	global_store_dwordx4 v[0:1], v[8:11], off offset:1088
	s_nop 1
	ds_read_b128 v[8:11], v230 offset:2336
	s_nop 0
	ds_read_b128 v[20:23], v230 offset:2352
	s_waitcnt lgkmcnt(0)
	v_pk_mul_f32 v[8:9], v[16:17], v[8:9]
	v_pk_mul_f32 v[10:11], v[18:19], v[10:11]
	s_waitcnt lgkmcnt(0)
	v_pk_mul_f32 v[14:15], v[14:15], v[20:21]
	v_pk_mul_f32 v[16:17], v[24:25], v[22:23]
	v_cvt_pk_bf16_f32 v8, v8, v9
	v_cvt_pk_bf16_f32 v9, v10, v11
	v_cvt_pk_bf16_f32 v10, v14, v15
	v_cvt_pk_bf16_f32 v11, v16, v17
	global_store_dwordx4 v[0:1], v[8:11], off offset:1104
	s_nop 1
	ds_read_b128 v[8:11], v230 offset:2368
	s_nop 0
	ds_read_b128 v[14:17], v230 offset:2384
	s_waitcnt lgkmcnt(0)
	v_pk_mul_f32 v[4:5], v[4:5], v[8:9]
	v_pk_mul_f32 v[6:7], v[6:7], v[10:11]
	s_waitcnt lgkmcnt(0)
	v_pk_mul_f32 v[8:9], v[2:3], v[14:15]
	v_pk_mul_f32 v[10:11], v[12:13], v[16:17]
	v_cvt_pk_bf16_f32 v2, v4, v5
	v_cvt_pk_bf16_f32 v3, v6, v7
	v_cvt_pk_bf16_f32 v4, v8, v9
	v_cvt_pk_bf16_f32 v5, v10, v11
	global_store_dwordx4 v[0:1], v[2:5], off offset:1120
	s_nop 1
	ds_read_b128 v[2:5], v230 offset:2400
	s_nop 0
	ds_read_b128 v[6:9], v230 offset:2416
	v_mov_b32_e32 v10, v88
	v_mov_b32_e32 v11, v84
	v_mov_b32_e32 v84, v89
	v_mov_b32_e32 v12, v90
	v_mov_b32_e32 v13, v86
	v_mov_b32_e32 v86, v91
	v_pk_mul_f32 v[10:11], v[10:11], v[32:33] op_sel_hi:[1,0]
	v_pk_mul_f32 v[14:15], v[84:85], v[32:33] op_sel_hi:[1,0]
	v_pk_mul_f32 v[12:13], v[12:13], v[32:33] op_sel_hi:[1,0]
	v_pk_mul_f32 v[16:17], v[86:87], v[32:33] op_sel_hi:[1,0]
	s_waitcnt lgkmcnt(0)
	v_pk_mul_f32 v[2:3], v[10:11], v[2:3]
	v_pk_mul_f32 v[4:5], v[14:15], v[4:5]
	s_waitcnt lgkmcnt(0)
	v_pk_mul_f32 v[6:7], v[12:13], v[6:7]
	v_pk_mul_f32 v[8:9], v[16:17], v[8:9]
	v_cvt_pk_bf16_f32 v2, v2, v3
	v_cvt_pk_bf16_f32 v3, v4, v5
	v_cvt_pk_bf16_f32 v4, v6, v7
	v_cvt_pk_bf16_f32 v5, v8, v9
	global_store_dwordx4 v[0:1], v[2:5], off offset:1136
	s_cbranch_scc1 .LBB0_747
